# K loops of gemm1, gemm2 and out: loop-edge rotation - the 7 of 10 loop-head fragment reads that do not clobber operands of the MFMAs behind the loop-end barrier are issued right after that barrier (an
# baseline (speedup 1.0000x reference)
; DI void gemm_kloop(const bf16_t* __restrict__ A, int lda, const bf16_t* __restrict__ B, int ldb, int K, bf16_t* sm,
;                    f32x4 (&acc)[4][4]) {
;     ...
;   __syncthreads();
;   GLOAD(ra0, rb0, 0)
;   GLOAD(ra1, rb1, 64)
;   SSTORE(ra0, rb0, 0)
;   __syncthreads();
; DI void gemm1_phase(const Params& p, int l, char* smem) {
;     ...
;       const int u = t - NT1;
;       const int lm = u >> 5, mt = (u >> 3) & 3, nt = u & 7;
;       gemm_kloop(p.memn + ((size_t)lm * 512 + mt * 128) * DM, DM, p.Wmem + ((size_t)lm * DM + nt * 128) * DM, DM, DM, sm, acc);
.LBB0_164:
	s_cmpk_gt_u32 s9, 0x1d3
	s_mov_b64 s[10:11], -1
	s_cbranch_scc0 .LBB0_334
	s_lshr_b32 s44, s8, 5
	s_lshl_b32 s12, s7, 11
	s_lshl_b64 s[10:11], s[44:45], 21
	s_and_b32 s12, s12, 0x1c0000
	s_lshl_b32 s14, s6, 11
	s_or_b32 s10, s10, s12
	s_lshl_b64 s[12:13], s[44:45], 20
	s_and_b32 s14, s14, 0xc0000
	s_or_b32 s12, s12, s14
	s_lshl_b32 s14, s9, 3
	v_readlane_b32 s15, v254, 20
	s_add_i32 s18, s14, s15
	s_load_dwordx2 s[16:17], s[0:1], 0x100
	s_load_dwordx2 s[14:15], s[0:1], 0x128
	s_lshr_b32 s44, s18, 5
	s_lshl_b32 s19, s18, 4
	s_and_b32 s19, s19, 0x180
	s_lshl_b64 s[20:21], s[44:45], 20
	v_mov_b32_e32 v68, v182
	s_waitcnt lgkmcnt(0)
	s_add_u32 s20, s14, s20
	s_addc_u32 s21, s15, s21
	v_lshlrev_b32_e32 v4, 3, v68
	s_lshl_b32 s22, s19, 11
	v_ashrrev_i32_e32 v6, 3, v68
	v_and_b32_e32 v7, 56, v4
	s_add_u32 s20, s20, s22
	v_lshl_or_b32 v4, v6, 10, v7
	v_mov_b32_e32 v5, v164
	s_addc_u32 s21, s21, 0
	v_lshlrev_b64 v[122:123], 1, v[4:5]
	s_lshl_b32 s18, s18, 7
	v_lshl_add_u64 v[4:5], s[20:21], 0, v[122:123]
	s_and_b32 s18, s18, 0x380
	s_lshl_b64 s[22:23], s[44:45], 21
	v_add_co_u32_e32 v8, vcc, s85, v4
	s_add_u32 s22, s16, s22
	s_nop 0
	v_addc_co_u32_e32 v9, vcc, 0, v5, vcc
	s_addc_u32 s23, s17, s23
	s_lshl_b32 s24, s18, 11
	v_add_co_u32_e32 v10, vcc, s88, v4
	s_add_u32 s22, s22, s24
	s_nop 0
	v_addc_co_u32_e32 v11, vcc, 0, v5, vcc
	s_addc_u32 s23, s23, 0
	v_add_co_u32_e32 v12, vcc, s89, v4
	v_lshl_add_u64 v[16:17], s[22:23], 0, v[122:123]
	s_nop 0
	v_addc_co_u32_e32 v13, vcc, 0, v5, vcc
	v_add_co_u32_e32 v18, vcc, s85, v16
	v_mul_lo_u32 v6, v6, s54
	s_nop 0
	v_addc_co_u32_e32 v19, vcc, 0, v17, vcc
	v_add_co_u32_e32 v20, vcc, s88, v16
	s_nop 1
	v_addc_co_u32_e32 v21, vcc, 0, v17, vcc
	v_add_co_u32_e32 v32, vcc, s89, v16
	s_barrier
	s_nop 0
	v_addc_co_u32_e32 v33, vcc, 0, v17, vcc
	global_load_dwordx4 v[36:39], v[4:5], off
	global_load_dwordx4 v[40:43], v[8:9], off
	global_load_dwordx4 v[44:47], v[10:11], off
	global_load_dwordx4 v[48:51], v[12:13], off
	global_load_dwordx4 v[52:55], v[16:17], off
	global_load_dwordx4 v[56:59], v[18:19], off
	global_load_dwordx4 v[60:63], v[20:21], off
	global_load_dwordx4 v[64:67], v[32:33], off
	v_lshl_add_u32 v131, v7, 1, v6
	global_load_dwordx4 v[4:7], v[4:5], off offset:128
	s_nop 0
	global_load_dwordx4 v[24:27], v[8:9], off offset:128
	s_nop 0
	global_load_dwordx4 v[8:11], v[10:11], off offset:128
	s_nop 0
	global_load_dwordx4 v[12:15], v[12:13], off offset:128
	s_nop 0
	global_load_dwordx4 v[28:31], v[16:17], off offset:128
	s_nop 0
	global_load_dwordx4 v[16:19], v[18:19], off offset:128
	s_nop 0
	global_load_dwordx4 v[20:23], v[20:21], off offset:128
	s_nop 0
	global_load_dwordx4 v[32:35], v[32:33], off offset:128
	v_and_b32_e32 v69, 15, v68
	v_lshrrev_b32_e32 v70, 1, v68
	s_mov_b32 s20, 0xfffffc0
	s_add_u32 s10, s16, s10
	s_addc_u32 s11, s17, s11
	s_add_u32 s12, s14, s12
	v_add_u32_e32 v132, 0x9000, v131
	s_addc_u32 s13, s15, s13
	s_mov_b32 s14, -2
	s_waitcnt vmcnt(15)
	ds_write_b128 v131, v[36:39]
	s_waitcnt vmcnt(14)
	ds_write_b128 v131, v[40:43] offset:4608
	s_waitcnt vmcnt(13)
	ds_write_b128 v131, v[44:47] offset:9216
	s_waitcnt vmcnt(12)
	ds_write_b128 v131, v[48:51] offset:13824
	s_waitcnt vmcnt(11)
	ds_write_b128 v131, v[52:55] offset:18432
	s_waitcnt vmcnt(10)
	ds_write_b128 v131, v[56:59] offset:23040
	s_waitcnt vmcnt(9)
	ds_write_b128 v131, v[60:63] offset:27648
	s_waitcnt vmcnt(8)
	ds_write_b128 v131, v[64:67] offset:32256
	v_and_or_b32 v37, v70, s20, v69
	v_and_b32_e32 v36, 48, v68
	v_mad_u64_u32 v[120:121], s[20:21], v37, s54, v[36:37]
	v_and_b32_e32 v37, 0x4f, v68
	v_mul_u32_u24_e32 v37, 0x48, v37
	v_lshl_add_u32 v121, v37, 1, v36
	v_mov_b32_e32 v36, 0
	v_mov_b32_e32 v37, v36
	v_mov_b32_e32 v38, v36
	v_mov_b32_e32 v39, v36
	v_mov_b32_e32 v92, v36
	v_mov_b32_e32 v93, v36
	v_mov_b32_e32 v94, v36
	v_mov_b32_e32 v95, v36
	v_mov_b32_e32 v40, v36
	v_mov_b32_e32 v41, v36
	v_mov_b32_e32 v42, v36
	v_mov_b32_e32 v43, v36
	v_mov_b32_e32 v44, v36
	v_mov_b32_e32 v45, v36
	v_mov_b32_e32 v46, v36
	v_mov_b32_e32 v47, v36
	v_mov_b32_e32 v48, v36
	v_mov_b32_e32 v49, v36
	v_mov_b32_e32 v50, v36
	v_mov_b32_e32 v51, v36
	v_mov_b32_e32 v52, v36
	v_mov_b32_e32 v53, v36
	v_mov_b32_e32 v54, v36
	v_mov_b32_e32 v55, v36
	v_mov_b32_e32 v56, v36
	v_mov_b32_e32 v57, v36
	v_mov_b32_e32 v58, v36
	v_mov_b32_e32 v59, v36
	v_mov_b32_e32 v60, v36
	v_mov_b32_e32 v61, v36
	v_mov_b32_e32 v62, v36
	v_mov_b32_e32 v63, v36
	v_mov_b32_e32 v64, v36
	v_mov_b32_e32 v65, v36
	v_mov_b32_e32 v66, v36
	v_mov_b32_e32 v67, v36
	v_mov_b32_e32 v68, v36
	v_mov_b32_e32 v69, v36
	v_mov_b32_e32 v70, v36
	v_mov_b32_e32 v71, v36
	v_mov_b32_e32 v72, v36
	v_mov_b32_e32 v73, v36
	v_mov_b32_e32 v74, v36
	v_mov_b32_e32 v75, v36
	v_mov_b32_e32 v76, v36
	v_mov_b32_e32 v77, v36
	v_mov_b32_e32 v78, v36
	v_mov_b32_e32 v79, v36
	v_mov_b32_e32 v80, v36
	v_mov_b32_e32 v81, v36
	v_mov_b32_e32 v82, v36
	v_mov_b32_e32 v83, v36
	v_mov_b32_e32 v84, v36
	v_mov_b32_e32 v85, v36
	v_mov_b32_e32 v86, v36
	v_mov_b32_e32 v87, v36
	v_mov_b32_e32 v88, v36
	v_mov_b32_e32 v89, v36
	v_mov_b32_e32 v90, v36
	v_mov_b32_e32 v91, v36
	v_mov_b32_e32 v96, v36
	v_mov_b32_e32 v97, v36
	v_mov_b32_e32 v98, v36
	v_mov_b32_e32 v99, v36
	s_waitcnt lgkmcnt(0)
	s_barrier
	ds_read_b128 v[134:137], v120
	ds_read_b128 v[138:141], v121 offset:18432
	ds_read_b128 v[142:145], v120 offset:64
	ds_read_b128 v[146:149], v121 offset:18496
	ds_read_b128 v[150:153], v121 offset:20736
	ds_read_b128 v[158:161], v121 offset:23040
	ds_read_b128 v[172:175], v121 offset:25344
; DI void gemm_kloop(const bf16_t* __restrict__ A, int lda, const bf16_t* __restrict__ B, int ldb, int K, bf16_t* sm,
;                    f32x4 (&acc)[4][4]) {
;     ...
;   __syncthreads();
;   GLOAD(ra0, rb0, 0)
;   GLOAD(ra1, rb1, 64)
;   SSTORE(ra0, rb0, 0)
;   __syncthreads();
;   for (int kt = 0; kt < nk - 2; kt += 2) {
;     GLOAD(ra0, rb0, (kt + 2) << 6)
;     COMPUTE(0)
;     SSTORE(ra1, rb1, 1)
;     __syncthreads();
;     GLOAD(ra1, rb1, (kt + 3) << 6)
;     COMPUTE(1)
;     SSTORE(ra0, rb0, 0)
;     __syncthreads();
.LBB0_166:
	ds_read_b128 v[154:157], v121 offset:20800
	ds_read_b128 v[168:171], v121 offset:23104
	ds_read_b128 v[176:179], v121 offset:25408
	s_waitcnt lgkmcnt(8)
	v_mfma_f32_16x16x32_bf16 v[96:99], v[134:137], v[138:141], v[96:99]
	v_lshl_add_u64 v[162:163], s[12:13], 0, v[122:123]
	v_add_co_u32_e32 v228, vcc, s85, v162
	s_waitcnt lgkmcnt(5)
	v_mfma_f32_16x16x32_bf16 v[88:91], v[134:137], v[150:153], v[88:91]
	v_addc_co_u32_e32 v229, vcc, 0, v163, vcc
	v_add_co_u32_e32 v230, vcc, s88, v162
	s_waitcnt lgkmcnt(3)
	v_mfma_f32_16x16x32_bf16 v[84:87], v[134:137], v[158:161], v[84:87]
	v_addc_co_u32_e32 v231, vcc, 0, v163, vcc
	v_add_co_u32_e32 v232, vcc, s89, v162
	s_waitcnt lgkmcnt(1)
	v_mfma_f32_16x16x32_bf16 v[80:83], v[134:137], v[172:175], v[80:83]
	ds_read_b128 v[134:137], v120 offset:2304
	ds_read_b128 v[208:211], v120 offset:2368
	v_lshl_add_u64 v[180:181], s[10:11], 0, v[122:123]
	v_addc_co_u32_e32 v233, vcc, 0, v163, vcc
	s_waitcnt lgkmcnt(1)
	v_mfma_f32_16x16x32_bf16 v[76:79], v[134:137], v[138:141], v[76:79]
	v_add_co_u32_e32 v234, vcc, s85, v180
	s_add_i32 s14, s14, 2
	v_mfma_f32_16x16x32_bf16 v[72:75], v[134:137], v[150:153], v[72:75]
	v_addc_co_u32_e32 v235, vcc, 0, v181, vcc
	v_add_co_u32_e32 v236, vcc, s88, v180
	v_mfma_f32_16x16x32_bf16 v[68:71], v[134:137], v[158:161], v[68:71]
	s_nop 0
	v_addc_co_u32_e32 v237, vcc, 0, v181, vcc
	v_add_co_u32_e32 v238, vcc, s89, v180
	v_mfma_f32_16x16x32_bf16 v[64:67], v[134:137], v[172:175], v[64:67]
	ds_read_b128 v[134:137], v120 offset:4608
	ds_read_b128 v[212:215], v120 offset:4672
	v_addc_co_u32_e32 v239, vcc, 0, v181, vcc
	s_waitcnt lgkmcnt(1)
	v_mfma_f32_16x16x32_bf16 v[60:63], v[134:137], v[138:141], v[60:63]
	s_add_u32 s10, s10, 0x100
	s_addc_u32 s11, s11, 0
	s_add_u32 s12, s12, 0x100
	v_mfma_f32_16x16x32_bf16 v[56:59], v[134:137], v[150:153], v[56:59]
	s_addc_u32 s13, s13, 0
	s_cmp_lt_u32 s14, 12
	v_mfma_f32_16x16x32_bf16 v[52:55], v[134:137], v[158:161], v[52:55]
	v_mfma_f32_16x16x32_bf16 v[48:51], v[134:137], v[172:175], v[48:51]
	ds_read_b128 v[134:137], v120 offset:6912
	ds_read_b128 v[216:219], v120 offset:6976
	s_waitcnt vmcnt(7)
	ds_write_b128 v131, v[4:7] offset:36864
	s_waitcnt vmcnt(6)
	ds_write_b128 v131, v[24:27] offset:41472
	s_waitcnt vmcnt(5)
	ds_write_b128 v131, v[8:11] offset:46080
	s_waitcnt vmcnt(4)
	ds_write_b128 v131, v[12:15] offset:50688
	s_waitcnt vmcnt(3)
	ds_write_b128 v131, v[28:31] offset:55296
	s_waitcnt lgkmcnt(6)
	v_mfma_f32_16x16x32_bf16 v[44:47], v[134:137], v[138:141], v[44:47]
	s_waitcnt vmcnt(2)
	ds_write_b128 v131, v[16:19] offset:59904
	s_waitcnt vmcnt(1)
	ds_write_b128 v131, v[20:23] offset:64512
	s_waitcnt vmcnt(0)
	ds_write_b128 v132, v[32:35] offset:32256
	global_load_dwordx4 v[138:141], v[180:181], off offset:256
	v_mfma_f32_16x16x32_bf16 v[40:43], v[134:137], v[150:153], v[40:43]
	v_mfma_f32_16x16x32_bf16 v[92:95], v[134:137], v[158:161], v[92:95]
	v_mfma_f32_16x16x32_bf16 v[36:39], v[134:137], v[172:175], v[36:39]
	global_load_dwordx4 v[134:137], v[162:163], off offset:256
	v_mfma_f32_16x16x32_bf16 v[96:99], v[142:145], v[146:149], v[96:99]
	v_mfma_f32_16x16x32_bf16 v[88:91], v[142:145], v[154:157], v[88:91]
	v_mfma_f32_16x16x32_bf16 v[4:7], v[142:145], v[168:171], v[84:87]
	v_mfma_f32_16x16x32_bf16 v[8:11], v[142:145], v[176:179], v[80:83]
	global_load_dwordx4 v[142:145], v[228:229], off offset:256
	global_load_dwordx4 v[150:153], v[230:231], off offset:256
	global_load_dwordx4 v[158:161], v[232:233], off offset:256
	v_mfma_f32_16x16x32_bf16 v[12:15], v[208:211], v[146:149], v[76:79]
	v_mfma_f32_16x16x32_bf16 v[16:19], v[208:211], v[154:157], v[72:75]
	v_mfma_f32_16x16x32_bf16 v[20:23], v[208:211], v[168:171], v[68:71]
	v_mfma_f32_16x16x32_bf16 v[24:27], v[208:211], v[176:179], v[64:67]
	v_mfma_f32_16x16x32_bf16 v[28:31], v[212:215], v[146:149], v[60:63]
	s_waitcnt lgkmcnt(8)
	v_mfma_f32_16x16x32_bf16 v[44:47], v[216:219], v[146:149], v[44:47]
	global_load_dwordx4 v[146:149], v[234:235], off offset:256
	global_load_dwordx4 v[172:175], v[236:237], off offset:256
	global_load_dwordx4 v[208:211], v[238:239], off offset:256
	s_waitcnt lgkmcnt(0)
	s_barrier
	ds_read_b128 v[60:63], v120 offset:36864
	v_mfma_f32_16x16x32_bf16 v[32:35], v[212:215], v[154:157], v[56:59]
	v_mfma_f32_16x16x32_bf16 v[40:43], v[216:219], v[154:157], v[40:43]
	v_mfma_f32_16x16x32_bf16 v[56:59], v[216:219], v[168:171], v[92:95]
	ds_read_b128 v[64:67], v121 offset:55296
	ds_read_b128 v[68:71], v120 offset:36928
	s_nop 0
	ds_read_b128 v[92:95], v121 offset:55360
	ds_read_b128 v[76:79], v121 offset:57600
	ds_read_b128 v[154:157], v121 offset:57664
	v_mfma_f32_16x16x32_bf16 v[52:55], v[212:215], v[168:171], v[52:55]
	ds_read_b128 v[84:87], v121 offset:59904
	ds_read_b128 v[168:171], v121 offset:59968
	v_mfma_f32_16x16x32_bf16 v[48:51], v[212:215], v[176:179], v[48:51]
	v_mfma_f32_16x16x32_bf16 v[36:39], v[216:219], v[176:179], v[36:39]
	s_waitcnt lgkmcnt(3)
	v_mfma_f32_16x16x32_bf16 v[80:83], v[60:63], v[76:79], v[88:91]
	s_nop 2
	ds_read_b128 v[88:91], v121 offset:62208
	ds_read_b128 v[176:179], v121 offset:62272
	v_mfma_f32_16x16x32_bf16 v[72:75], v[60:63], v[64:67], v[96:99]
	s_waitcnt lgkmcnt(3)
	v_mfma_f32_16x16x32_bf16 v[4:7], v[60:63], v[84:87], v[4:7]
	s_waitcnt lgkmcnt(1)
	v_mfma_f32_16x16x32_bf16 v[8:11], v[60:63], v[88:91], v[8:11]
	ds_read_b128 v[60:63], v120 offset:39168
	ds_read_b128 v[212:215], v120 offset:39232
	s_waitcnt lgkmcnt(1)
	v_mfma_f32_16x16x32_bf16 v[12:15], v[60:63], v[64:67], v[12:15]
	v_mfma_f32_16x16x32_bf16 v[16:19], v[60:63], v[76:79], v[16:19]
	v_mfma_f32_16x16x32_bf16 v[20:23], v[60:63], v[84:87], v[20:23]
	v_mfma_f32_16x16x32_bf16 v[24:27], v[60:63], v[88:91], v[24:27]
	ds_read_b128 v[60:63], v120 offset:41472
	ds_read_b128 v[216:219], v120 offset:41536
	s_waitcnt lgkmcnt(1)
; DI void gemm_kloop(const bf16_t* __restrict__ A, int lda, const bf16_t* __restrict__ B, int ldb, int K, bf16_t* sm,
;                    f32x4 (&acc)[4][4]) {
;     ...
;   __syncthreads();
;   GLOAD(ra0, rb0, 0)
;   GLOAD(ra1, rb1, 64)
;   SSTORE(ra0, rb0, 0)
;   __syncthreads();
;   for (int kt = 0; kt < nk - 2; kt += 2) {
;     GLOAD(ra0, rb0, (kt + 2) << 6)
;     COMPUTE(0)
;     SSTORE(ra1, rb1, 1)
;     __syncthreads();
;     GLOAD(ra1, rb1, (kt + 3) << 6)
;     COMPUTE(1)
;     SSTORE(ra0, rb0, 0)
;     __syncthreads();
;   }
;   COMPUTE(0)
;   SSTORE(ra1, rb1, 1)
;   __syncthreads();
;   COMPUTE(1)
	v_mfma_f32_16x16x32_bf16 v[28:31], v[60:63], v[64:67], v[28:31]
	v_mfma_f32_16x16x32_bf16 v[32:35], v[60:63], v[76:79], v[32:35]
	v_mfma_f32_16x16x32_bf16 v[52:55], v[60:63], v[84:87], v[52:55]
	v_mfma_f32_16x16x32_bf16 v[48:51], v[60:63], v[88:91], v[48:51]
	ds_read_b128 v[60:63], v120 offset:43776
	ds_read_b128 v[220:223], v120 offset:43840
	s_waitcnt lgkmcnt(1)
	v_mfma_f32_16x16x32_bf16 v[44:47], v[60:63], v[64:67], v[44:47]
	v_mfma_f32_16x16x32_bf16 v[40:43], v[60:63], v[76:79], v[40:43]
	v_mfma_f32_16x16x32_bf16 v[224:227], v[60:63], v[84:87], v[56:59]
	v_mfma_f32_16x16x32_bf16 v[36:39], v[60:63], v[88:91], v[36:39]
	v_mfma_f32_16x16x32_bf16 v[96:99], v[68:71], v[92:95], v[72:75]
	v_mfma_f32_16x16x32_bf16 v[88:91], v[68:71], v[154:157], v[80:83]
	v_mfma_f32_16x16x32_bf16 v[84:87], v[68:71], v[168:171], v[4:7]
	v_mfma_f32_16x16x32_bf16 v[80:83], v[68:71], v[176:179], v[8:11]
	s_nop 1
	global_load_dwordx4 v[4:7], v[162:163], off offset:384
	v_mfma_f32_16x16x32_bf16 v[76:79], v[212:215], v[92:95], v[12:15]
	v_mfma_f32_16x16x32_bf16 v[72:75], v[212:215], v[154:157], v[16:19]
	v_mfma_f32_16x16x32_bf16 v[68:71], v[212:215], v[168:171], v[20:23]
	v_mfma_f32_16x16x32_bf16 v[64:67], v[212:215], v[176:179], v[24:27]
	s_nop 2
	global_load_dwordx4 v[24:27], v[228:229], off offset:384
	global_load_dwordx4 v[8:11], v[230:231], off offset:384
	global_load_dwordx4 v[12:15], v[232:233], off offset:384
	v_mfma_f32_16x16x32_bf16 v[60:63], v[216:219], v[92:95], v[28:31]
	s_nop 2
	global_load_dwordx4 v[28:31], v[180:181], off offset:384
	global_load_dwordx4 v[16:19], v[234:235], off offset:384
	global_load_dwordx4 v[20:23], v[236:237], off offset:384
	v_mfma_f32_16x16x32_bf16 v[56:59], v[216:219], v[154:157], v[32:35]
	s_nop 2
	global_load_dwordx4 v[32:35], v[238:239], off offset:384
	v_mfma_f32_16x16x32_bf16 v[52:55], v[216:219], v[168:171], v[52:55]
	s_waitcnt vmcnt(14)
	ds_write_b128 v131, v[134:137]
	ds_write_b128 v131, v[138:141] offset:18432
	s_waitcnt vmcnt(13)
	ds_write_b128 v131, v[142:145] offset:4608
	s_waitcnt vmcnt(12)
	ds_write_b128 v131, v[150:153] offset:9216
	s_waitcnt vmcnt(11)
	ds_write_b128 v131, v[158:161] offset:13824
	s_waitcnt vmcnt(10)
	ds_write_b128 v131, v[146:149] offset:23040
	s_waitcnt vmcnt(9)
	ds_write_b128 v131, v[172:175] offset:27648
	s_waitcnt vmcnt(8)
	ds_write_b128 v131, v[208:211] offset:32256
	s_waitcnt lgkmcnt(0)
	s_barrier
	ds_read_b128 v[134:137], v120
	ds_read_b128 v[138:141], v121 offset:18432
	ds_read_b128 v[142:145], v120 offset:64
	ds_read_b128 v[146:149], v121 offset:18496
	ds_read_b128 v[150:153], v121 offset:20736
	ds_read_b128 v[158:161], v121 offset:23040
	ds_read_b128 v[172:175], v121 offset:25344
	v_mfma_f32_16x16x32_bf16 v[48:51], v[216:219], v[176:179], v[48:51]
	v_mfma_f32_16x16x32_bf16 v[44:47], v[220:223], v[92:95], v[44:47]
	v_mfma_f32_16x16x32_bf16 v[40:43], v[220:223], v[154:157], v[40:43]
	v_mfma_f32_16x16x32_bf16 v[92:95], v[220:223], v[168:171], v[224:227]
	v_mfma_f32_16x16x32_bf16 v[36:39], v[220:223], v[176:179], v[36:39]
	s_cbranch_scc1 .LBB0_166
	ds_read_b128 v[134:137], v120
	ds_read_b128 v[138:141], v121 offset:18432
	ds_read_b128 v[142:145], v121 offset:20736
	ds_read_b128 v[146:149], v121 offset:23040
	ds_read_b128 v[150:153], v121 offset:25344
	s_movk_i32 s10, 0xc0
	s_waitcnt lgkmcnt(3)
	v_mfma_f32_16x16x32_bf16 v[96:99], v[134:137], v[138:141], v[96:99]
	s_mov_b64 s[20:21], 0x7286800
	s_cmpk_gt_u32 s18, 0x1ff
	s_cselect_b64 s[16:17], -1, 0
	s_waitcnt lgkmcnt(2)
	v_mfma_f32_16x16x32_bf16 v[88:91], v[134:137], v[142:145], v[88:91]
	s_and_b64 vcc, exec, s[16:17]
	s_waitcnt lgkmcnt(1)
	v_mfma_f32_16x16x32_bf16 v[84:87], v[134:137], v[146:149], v[84:87]
	s_waitcnt lgkmcnt(0)
	v_mfma_f32_16x16x32_bf16 v[80:83], v[134:137], v[150:153], v[80:83]
	ds_read_b128 v[134:137], v120 offset:2304
	s_waitcnt lgkmcnt(0)
	v_mfma_f32_16x16x32_bf16 v[76:79], v[134:137], v[138:141], v[76:79]
	v_mfma_f32_16x16x32_bf16 v[72:75], v[134:137], v[142:145], v[72:75]
	v_mfma_f32_16x16x32_bf16 v[68:71], v[134:137], v[146:149], v[68:71]
	v_mfma_f32_16x16x32_bf16 v[64:67], v[134:137], v[150:153], v[64:67]
	ds_read_b128 v[134:137], v120 offset:4608
	s_waitcnt lgkmcnt(0)
	v_mfma_f32_16x16x32_bf16 v[60:63], v[134:137], v[138:141], v[60:63]
	v_mfma_f32_16x16x32_bf16 v[56:59], v[134:137], v[142:145], v[56:59]
	v_mfma_f32_16x16x32_bf16 v[52:55], v[134:137], v[146:149], v[52:55]
	v_mfma_f32_16x16x32_bf16 v[48:51], v[134:137], v[150:153], v[48:51]
	ds_read_b128 v[134:137], v120 offset:6912
	s_waitcnt lgkmcnt(0)
	v_mfma_f32_16x16x32_bf16 v[44:47], v[134:137], v[138:141], v[44:47]
	ds_read_b128 v[138:141], v120 offset:64
	v_mfma_f32_16x16x32_bf16 v[40:43], v[134:137], v[142:145], v[40:43]
	ds_read_b128 v[142:145], v121 offset:20800
	v_mfma_f32_16x16x32_bf16 v[92:95], v[134:137], v[146:149], v[92:95]
	ds_read_b128 v[146:149], v121 offset:23104
	v_mfma_f32_16x16x32_bf16 v[36:39], v[134:137], v[150:153], v[36:39]
	ds_read_b128 v[134:137], v121 offset:18496
	ds_read_b128 v[150:153], v121 offset:25408
	s_waitcnt lgkmcnt(1)
	v_mfma_f32_16x16x32_bf16 v[96:99], v[138:141], v[134:137], v[96:99]
	v_mfma_f32_16x16x32_bf16 v[88:91], v[138:141], v[142:145], v[88:91]
	v_mfma_f32_16x16x32_bf16 v[84:87], v[138:141], v[146:149], v[84:87]
	s_waitcnt lgkmcnt(0)
	v_mfma_f32_16x16x32_bf16 v[80:83], v[138:141], v[150:153], v[80:83]
	ds_read_b128 v[138:141], v120 offset:2368
	s_waitcnt lgkmcnt(0)
	v_mfma_f32_16x16x32_bf16 v[76:79], v[138:141], v[134:137], v[76:79]
	v_mfma_f32_16x16x32_bf16 v[72:75], v[138:141], v[142:145], v[72:75]
	v_mfma_f32_16x16x32_bf16 v[68:71], v[138:141], v[146:149], v[68:71]
	v_mfma_f32_16x16x32_bf16 v[64:67], v[138:141], v[150:153], v[64:67]
	ds_read_b128 v[138:141], v120 offset:4672
	s_waitcnt lgkmcnt(0)
	v_mfma_f32_16x16x32_bf16 v[60:63], v[138:141], v[134:137], v[60:63]
	v_mfma_f32_16x16x32_bf16 v[56:59], v[138:141], v[142:145], v[56:59]
	v_mfma_f32_16x16x32_bf16 v[52:55], v[138:141], v[146:149], v[52:55]
	v_mfma_f32_16x16x32_bf16 v[48:51], v[138:141], v[150:153], v[48:51]
	ds_read_b128 v[138:141], v120 offset:6976
	s_waitcnt vmcnt(7)
	ds_write_b128 v131, v[4:7] offset:36864
	s_waitcnt vmcnt(6)
	ds_write_b128 v131, v[24:27] offset:41472
	s_waitcnt vmcnt(5)
	ds_write_b128 v131, v[8:11] offset:46080
	s_waitcnt vmcnt(4)
	ds_write_b128 v131, v[12:15] offset:50688
	s_waitcnt vmcnt(3)
	ds_write_b128 v131, v[28:31] offset:55296
	s_waitcnt vmcnt(2)
	ds_write_b128 v131, v[16:19] offset:59904
	s_waitcnt vmcnt(1)
	ds_write_b128 v131, v[20:23] offset:64512
	s_waitcnt vmcnt(0)
	ds_write_b128 v132, v[32:35] offset:32256
	s_waitcnt lgkmcnt(0)
	s_barrier
; DI bf16_t f2bf(float f) { return (bf16_t)(pack2(f, f) & 0xFFFFu); }
; DI void gemm_kloop(const bf16_t* __restrict__ A, int lda, const bf16_t* __restrict__ B, int ldb, int K, bf16_t* sm,
;                    f32x4 (&acc)[4][4]) {
;     ...
;   COMPUTE(1)
;   __syncthreads();
; DI void gemm1_phase(const Params& p, int l, char* smem) {
;     ...
; #pragma unroll
;       for (int i = 0; i < 4; i++)
; #pragma unroll
;         for (int r = 0; r < 4; r++) {
;           const int row = mt * 128 + wm * 64 + i * 16 + g4 * 4 + r;
;           const int bm = row >> 8, m = row & 255;
; #pragma unroll
;           for (int jn = 0; jn < 4; jn++) {
;             const int n = nt * 128 + wn * 64 + jn * 16 + cl;
;             const float v = acc[i][jn][r];
;             if (n < 512) {
;               p.out[O_MKP + ((size_t)(lm * 2 + bm) * 256 + m) * 512 + n] = v;
;             } else {
;               const int n2 = n - 512;
;               p.out[O_MVP + ((size_t)(lm * 2 + bm) * 256 + m) * 512 + n2] = v;
;               p.pmvT[((size_t)((lm * 2 + bm) * 4 + (n2 >> 7)) * 128 + (n2 & 127)) * 256 + m] = f2bf(v);
;             }
;           }
	ds_read_b128 v[4:7], v120 offset:36864
	ds_read_b128 v[8:11], v121 offset:55296
	v_mfma_f32_16x16x32_bf16 v[12:15], v[138:141], v[150:153], v[36:39]
	ds_read_b128 v[20:23], v121 offset:57600
	ds_read_b128 v[28:31], v121 offset:59904
	s_nop 0
	ds_read_b128 v[36:39], v121 offset:62208
	s_waitcnt lgkmcnt(3)
	v_mfma_f32_16x16x32_bf16 v[16:19], v[4:7], v[8:11], v[96:99]
	ds_read_b128 v[152:155], v121 offset:57664
	ds_read_b128 v[156:159], v121 offset:59968
	ds_read_b128 v[160:163], v121 offset:62272
	s_waitcnt lgkmcnt(5)
	v_mfma_f32_16x16x32_bf16 v[24:27], v[4:7], v[20:23], v[88:91]
	s_waitcnt lgkmcnt(4)
	v_mfma_f32_16x16x32_bf16 v[32:35], v[4:7], v[28:31], v[84:87]
	s_waitcnt lgkmcnt(3)
	v_mfma_f32_16x16x32_bf16 v[80:83], v[4:7], v[36:39], v[80:83]
	ds_read_b128 v[4:7], v120 offset:39168
	s_waitcnt lgkmcnt(0)
	v_mfma_f32_16x16x32_bf16 v[76:79], v[4:7], v[8:11], v[76:79]
	v_mfma_f32_16x16x32_bf16 v[72:75], v[4:7], v[20:23], v[72:75]
	v_mfma_f32_16x16x32_bf16 v[68:71], v[4:7], v[28:31], v[68:71]
	v_mfma_f32_16x16x32_bf16 v[84:87], v[4:7], v[36:39], v[64:67]
	ds_read_b128 v[4:7], v120 offset:41472
	v_mfma_f32_16x16x32_bf16 v[44:47], v[138:141], v[134:137], v[44:47]
	v_mfma_f32_16x16x32_bf16 v[40:43], v[138:141], v[142:145], v[40:43]
	v_mfma_f32_16x16x32_bf16 v[92:95], v[138:141], v[146:149], v[92:95]
	s_waitcnt lgkmcnt(0)
	v_mfma_f32_16x16x32_bf16 v[140:143], v[4:7], v[36:39], v[48:51]
	s_nop 2
	ds_read_b128 v[48:51], v120 offset:43776
	v_mfma_f32_16x16x32_bf16 v[88:91], v[4:7], v[8:11], v[60:63]
	v_mfma_f32_16x16x32_bf16 v[132:135], v[4:7], v[20:23], v[56:59]
	s_waitcnt lgkmcnt(0)
	v_mfma_f32_16x16x32_bf16 v[144:147], v[48:51], v[8:11], v[44:47]
	v_mfma_f32_16x16x32_bf16 v[8:11], v[48:51], v[20:23], v[40:43]
	ds_read_b128 v[20:23], v120 offset:36928
	v_mfma_f32_16x16x32_bf16 v[148:151], v[48:51], v[36:39], v[12:15]
	s_nop 2
	ds_read_b128 v[12:15], v121 offset:55360
	s_waitcnt lgkmcnt(0)
	v_mfma_f32_16x16x32_bf16 v[60:63], v[20:23], v[12:15], v[16:19]
	s_nop 2
	ds_read_b128 v[16:19], v120 offset:39232
	v_mfma_f32_16x16x32_bf16 v[136:139], v[4:7], v[28:31], v[52:55]
	v_mfma_f32_16x16x32_bf16 v[4:7], v[48:51], v[28:31], v[92:95]
	v_mfma_f32_16x16x32_bf16 v[64:67], v[20:23], v[152:155], v[24:27]
	v_mfma_f32_16x16x32_bf16 v[56:59], v[20:23], v[156:159], v[32:35]
	v_mfma_f32_16x16x32_bf16 v[52:55], v[20:23], v[160:163], v[80:83]
	ds_read_b128 v[20:23], v120 offset:41536
	s_waitcnt lgkmcnt(1)
	v_mfma_f32_16x16x32_bf16 v[48:51], v[16:19], v[12:15], v[76:79]
	s_nop 2
	ds_read_b128 v[78:81], v120 offset:43840
	v_mfma_f32_16x16x32_bf16 v[44:47], v[16:19], v[152:155], v[72:75]
	s_waitcnt lgkmcnt(0)
	s_barrier
	v_mfma_f32_16x16x32_bf16 v[36:39], v[16:19], v[156:159], v[68:71]
	s_load_dwordx2 s[14:15], s[0:1], 0xe8
	s_load_dwordx2 s[12:13], s[0:1], 0x120
	v_mov_b32_e32 v75, v164
	v_lshlrev_b32_e32 v70, 1, v102
	v_mfma_f32_16x16x32_bf16 v[40:43], v[16:19], v[160:163], v[84:87]
	v_add_u32_e32 v16, s19, v125
	v_ashrrev_i32_e32 v17, 8, v16
	v_and_or_b32 v123, v16, s10, v126
	v_lshl_add_u32 v96, s44, 1, v17
	v_ashrrev_i32_e32 v97, 31, v96
	v_lshlrev_b32_e32 v74, 11, v123
	s_waitcnt lgkmcnt(0)
	v_lshl_add_u64 v[16:17], s[14:15], 0, v[74:75]
	v_lshlrev_b64 v[76:77], 19, v[96:97]
	v_lshl_add_u64 v[16:17], v[16:17], 0, v[76:77]
	v_mfma_f32_16x16x32_bf16 v[32:35], v[20:23], v[12:15], v[88:91]
	v_lshl_add_u64 v[94:95], v[16:17], 0, s[20:21]
	v_or_b32_e32 v84, s18, v129
	v_add_u32_e32 v72, 0xfffffe00, v84
	v_mfma_f32_16x16x32_bf16 v[28:31], v[20:23], v[152:155], v[132:135]
	v_lshlrev_b32_e32 v122, 2, v96
	s_mov_b64 s[10:11], -1
	v_lshrrev_b32_e32 v131, 7, v72
	v_mfma_f32_16x16x32_bf16 v[24:27], v[20:23], v[156:159], v[136:139]
	v_lshlrev_b32_e32 v68, 1, v123
	v_mfma_f32_16x16x32_bf16 v[20:23], v[20:23], v[160:163], v[140:143]
	v_mfma_f32_16x16x32_bf16 v[16:19], v[78:81], v[12:15], v[144:147]
	v_mfma_f32_16x16x32_bf16 v[12:15], v[78:81], v[152:155], v[8:11]
	v_mfma_f32_16x16x32_bf16 v[8:11], v[78:81], v[156:159], v[4:7]
	v_mfma_f32_16x16x32_bf16 v[4:7], v[78:81], v[160:163], v[148:151]
	s_cbranch_vccz .LBB0_169
	v_mov_b32_e32 v73, v164
	v_lshl_add_u64 v[78:79], v[72:73], 2, v[94:95]
	global_store_dword v[78:79], v60, off
	v_add_u32_e32 v78, v131, v122
	v_ashrrev_i32_e32 v79, 31, v78
	v_lshlrev_b64 v[78:79], 16, v[78:79]
	v_lshl_add_u64 v[78:79], s[12:13], 0, v[78:79]
	v_mov_b32_e32 v71, v164
	v_lshl_add_u64 v[78:79], v[78:79], 0, v[70:71]
	v_mov_b32_e32 v69, v164
	v_cvt_pk_bf16_f32 v73, v60, s0
	v_lshl_add_u64 v[78:79], v[78:79], 0, v[68:69]
	global_store_short v[78:79], v73, off
	s_mov_b64 s[10:11], 0

; DI void gemm_kloop(const bf16_t* __restrict__ A, int lda, const bf16_t* __restrict__ B, int ldb, int K, bf16_t* sm,
;                    f32x4 (&acc)[4][4]) {
;     ...
;   __syncthreads();
;   GLOAD(ra0, rb0, 0)
;   GLOAD(ra1, rb1, 64)
;   SSTORE(ra0, rb0, 0)
;   __syncthreads();
; DI bool xcd_tile(int e, int NNT, int& mt, int& nt) {
;   const int xcd = blockIdx.x & 7;
;   const int per_mb = 9 * NNT;
;   if (e >= 2 * per_mb) return false;
;   const int mb = e >= per_mb ? 1 : 0;
;   int r = e - mb * per_mb;
;   const int full = NNT >> 3, rem = NNT & 7;
;   int nb = r / 72;
;   int w = 8;
;   if (nb >= full) { nb = full; w = rem; }
;   r -= nb * 72;
;   const int mi = r / w, ni = r - mi * w;
;   mt = xcd * 18 + mb * 9 + mi;
;   nt = nb * 8 + ni;
;   return true;
; }
.LBB0_1700:
	s_cmpk_lt_u32 s16, 0x144
	s_cselect_b32 s8, 0, 0xfffffebc
	s_cselect_b32 s10, 0, 9
	s_add_i32 s18, s8, s16
	s_mul_i32 s8, s18, 0xe39
	s_lshr_b32 s9, s8, 31
	s_ashr_i32 s8, s8, 18
	s_add_i32 s8, s8, s9
	s_min_i32 s19, s8, 4
	s_mul_i32 s8, s19, 0xffffffb8
	s_add_i32 s11, s8, s18
	s_ashr_i32 s8, s11, 30
	s_or_b32 s12, s8, 1
	s_cmpk_lt_i32 s18, 0x120
	s_cselect_b32 s8, 8, 4
	v_cvt_f32_ubyte0_e32 v5, s8
	v_cvt_f32_i32_e32 v4, s11
	v_rcp_iflag_f32_e32 v6, v5
	s_cselect_b32 s13, 3, 2
	v_mov_b32_e32 v7, v182
	v_mul_f32_e32 v6, v4, v6
	v_trunc_f32_e32 v6, v6
	v_fma_f32 v4, -v6, v5, v4
	v_cvt_i32_f32_e32 v6, v6
	v_cmp_ge_f32_e64 s[8:9], |v4|, v5
	s_and_b64 s[8:9], s[8:9], exec
	s_cselect_b32 s8, s12, 0
	v_readfirstlane_b32 s9, v6
	s_add_i32 s9, s9, s8
	s_sext_i32_i16 s8, s9
	v_readlane_b32 s9, v254, 19
	s_add_i32 s9, s10, s9
	s_lshl_b32 s20, s8, s13
	s_add_i32 s8, s9, s8
	s_lshl_b32 s9, s19, 3
	s_add_i32 s11, s11, s9
	s_ashr_i32 s9, s8, 31
	v_lshlrev_b32_e32 v4, 3, v7
	s_sub_i32 s12, s11, s20
	s_lshl_b64 s[10:11], s[8:9], 18
	v_ashrrev_i32_e32 v14, 3, v7
	v_and_b32_e32 v15, 56, v4
	s_add_u32 s10, s6, s10
	v_lshl_or_b32 v4, v14, 10, v15
	v_mov_b32_e32 v5, v164
	s_addc_u32 s11, s7, s11
	s_lshl_b32 s17, s12, 7
	v_readlane_b32 s12, v254, 51
	v_lshlrev_b64 v[104:105], 1, v[4:5]
	s_ashr_i32 s9, s17, 31
	s_mulk_i32 s12, 0x1200
	v_lshl_add_u64 v[4:5], s[10:11], 0, v[104:105]
	v_readlane_b32 s13, v254, 52
	s_add_u32 s12, s17, s12
	v_add_co_u32_e32 v8, vcc, s85, v4
	s_addc_u32 s13, s9, 0
	s_nop 0
	v_addc_co_u32_e32 v9, vcc, 0, v5, vcc
	s_lshl_b64 s[12:13], s[12:13], 11
	v_add_co_u32_e32 v10, vcc, s88, v4
	s_add_u32 s12, s4, s12
	s_nop 0
	v_addc_co_u32_e32 v11, vcc, 0, v5, vcc
	s_addc_u32 s13, s5, s13
	v_add_co_u32_e32 v12, vcc, s89, v4
	v_lshl_add_u64 v[16:17], s[12:13], 0, v[104:105]
	s_nop 0
	v_addc_co_u32_e32 v13, vcc, 0, v5, vcc
	v_add_co_u32_e32 v18, vcc, s85, v16
	v_and_b32_e32 v22, 15, v7
	s_nop 0
	v_addc_co_u32_e32 v19, vcc, 0, v17, vcc
	v_add_co_u32_e32 v20, vcc, s88, v16
	v_lshrrev_b32_e32 v23, 1, v7
	s_nop 0
	v_addc_co_u32_e32 v21, vcc, 0, v17, vcc
	v_and_b32_e32 v6, 48, v7
	v_and_b32_e32 v7, 0x4f, v7
	s_mov_b32 s9, 0xfffffc0
	v_add_co_u32_e32 v32, vcc, s89, v16
	v_and_or_b32 v22, v23, s9, v22
	v_mul_u32_u24_e32 v7, 0x48, v7
	v_addc_co_u32_e32 v33, vcc, 0, v17, vcc
	v_mul_lo_u32 v14, v14, s54
	v_mad_u64_u32 v[102:103], s[12:13], v22, s54, v[6:7]
	s_barrier
	global_load_dwordx4 v[36:39], v[4:5], off
	global_load_dwordx4 v[40:43], v[8:9], off
	global_load_dwordx4 v[44:47], v[10:11], off
	global_load_dwordx4 v[48:51], v[12:13], off
	global_load_dwordx4 v[52:55], v[16:17], off
	global_load_dwordx4 v[56:59], v[18:19], off
	global_load_dwordx4 v[60:63], v[20:21], off
	global_load_dwordx4 v[64:67], v[32:33], off
	v_lshl_add_u32 v107, v15, 1, v14
	v_lshl_add_u32 v103, v7, 1, v6
	global_load_dwordx4 v[4:7], v[4:5], off offset:128
	s_nop 0
	global_load_dwordx4 v[24:27], v[8:9], off offset:128
	s_nop 0
	global_load_dwordx4 v[8:11], v[10:11], off offset:128
	s_nop 0
	global_load_dwordx4 v[12:15], v[12:13], off offset:128
	s_nop 0
	global_load_dwordx4 v[28:31], v[16:17], off offset:128
	s_nop 0
	global_load_dwordx4 v[16:19], v[18:19], off offset:128
	s_nop 0
	global_load_dwordx4 v[20:23], v[20:21], off offset:128
	s_nop 0
	global_load_dwordx4 v[32:35], v[32:33], off offset:128
	s_sub_i32 s9, s18, s20
	s_lshl_b32 s12, s19, 6
	s_sub_i32 s9, s9, s12
	s_lshl_b32 s12, s9, 7
	s_ashr_i32 s13, s12, 31
	s_lshl_b64 s[12:13], s[12:13], 11
	s_add_u32 s12, s14, s12
	v_add_u32_e32 v108, 0x9000, v107
	s_addc_u32 s13, s15, s13
	s_mov_b32 s9, -2
	s_waitcnt vmcnt(15)
	ds_write_b128 v107, v[36:39]
	s_waitcnt vmcnt(14)
	ds_write_b128 v107, v[40:43] offset:4608
	s_waitcnt vmcnt(13)
	ds_write_b128 v107, v[44:47] offset:9216
	s_waitcnt vmcnt(12)
	ds_write_b128 v107, v[48:51] offset:13824
	s_waitcnt vmcnt(11)
	ds_write_b128 v107, v[52:55] offset:18432
	s_waitcnt vmcnt(10)
	ds_write_b128 v107, v[56:59] offset:23040
	s_waitcnt vmcnt(9)
	ds_write_b128 v107, v[60:63] offset:27648
	s_waitcnt vmcnt(8)
	ds_write_b128 v107, v[64:67] offset:32256
	v_mov_b32_e32 v36, 0
	v_mov_b32_e32 v37, v36
	v_mov_b32_e32 v38, v36
	v_mov_b32_e32 v39, v36
	v_mov_b32_e32 v92, v36
	v_mov_b32_e32 v93, v36
	v_mov_b32_e32 v94, v36
	v_mov_b32_e32 v95, v36
	v_mov_b32_e32 v40, v36
	v_mov_b32_e32 v41, v36
	v_mov_b32_e32 v42, v36
	v_mov_b32_e32 v43, v36
	v_mov_b32_e32 v44, v36
	v_mov_b32_e32 v45, v36
	v_mov_b32_e32 v46, v36
	v_mov_b32_e32 v47, v36
	v_mov_b32_e32 v48, v36
	v_mov_b32_e32 v49, v36
	v_mov_b32_e32 v50, v36
	v_mov_b32_e32 v51, v36
	v_mov_b32_e32 v52, v36
	v_mov_b32_e32 v53, v36
	v_mov_b32_e32 v54, v36
	v_mov_b32_e32 v55, v36
	v_mov_b32_e32 v56, v36
	v_mov_b32_e32 v57, v36
	v_mov_b32_e32 v58, v36
	v_mov_b32_e32 v59, v36
	v_mov_b32_e32 v60, v36
	v_mov_b32_e32 v61, v36
	v_mov_b32_e32 v62, v36
	v_mov_b32_e32 v63, v36
	v_mov_b32_e32 v64, v36
	v_mov_b32_e32 v65, v36
	v_mov_b32_e32 v66, v36
	v_mov_b32_e32 v67, v36
	v_mov_b32_e32 v68, v36
	v_mov_b32_e32 v69, v36
	v_mov_b32_e32 v70, v36
	v_mov_b32_e32 v71, v36
	v_mov_b32_e32 v72, v36
	v_mov_b32_e32 v73, v36
	v_mov_b32_e32 v74, v36
	v_mov_b32_e32 v75, v36
	v_mov_b32_e32 v76, v36
	v_mov_b32_e32 v77, v36
	v_mov_b32_e32 v78, v36
	v_mov_b32_e32 v79, v36
	v_mov_b32_e32 v80, v36
	v_mov_b32_e32 v81, v36
	v_mov_b32_e32 v82, v36
	v_mov_b32_e32 v83, v36
	v_mov_b32_e32 v84, v36
	v_mov_b32_e32 v85, v36
	v_mov_b32_e32 v86, v36
	v_mov_b32_e32 v87, v36
	v_mov_b32_e32 v88, v36
	v_mov_b32_e32 v89, v36
	v_mov_b32_e32 v90, v36
	v_mov_b32_e32 v91, v36
	v_mov_b32_e32 v96, v36
	v_mov_b32_e32 v97, v36
	v_mov_b32_e32 v98, v36
	v_mov_b32_e32 v99, v36
	s_waitcnt lgkmcnt(0)
	s_barrier
	ds_read_b128 v[110:113], v102
	ds_read_b128 v[114:117], v103 offset:18432
	ds_read_b128 v[118:121], v102 offset:64
	ds_read_b128 v[122:125], v103 offset:18496
	ds_read_b128 v[126:129], v103 offset:20736
	ds_read_b128 v[134:137], v103 offset:23040
	ds_read_b128 v[142:145], v103 offset:25344
; DI void gemm_kloop(const bf16_t* __restrict__ A, int lda, const bf16_t* __restrict__ B, int ldb, int K, bf16_t* sm,
;                    f32x4 (&acc)[4][4]) {
;     ...
;   __syncthreads();
;   GLOAD(ra0, rb0, 0)
;   GLOAD(ra1, rb1, 64)
;   SSTORE(ra0, rb0, 0)
;   __syncthreads();
;   for (int kt = 0; kt < nk - 2; kt += 2) {
;     GLOAD(ra0, rb0, (kt + 2) << 6)
;     COMPUTE(0)
;     SSTORE(ra1, rb1, 1)
;     __syncthreads();
;     GLOAD(ra1, rb1, (kt + 3) << 6)
;     COMPUTE(1)
;     SSTORE(ra0, rb0, 0)
;     __syncthreads();
.LBB0_1701:
	ds_read_b128 v[130:133], v103 offset:20800
	ds_read_b128 v[138:141], v103 offset:23104
	ds_read_b128 v[146:149], v103 offset:25408
	s_waitcnt lgkmcnt(8)
	v_mfma_f32_16x16x32_bf16 v[96:99], v[110:113], v[114:117], v[96:99]
	v_lshl_add_u64 v[162:163], s[10:11], 0, v[104:105]
	v_add_co_u32_e32 v178, vcc, s85, v162
	s_waitcnt lgkmcnt(5)
	v_mfma_f32_16x16x32_bf16 v[88:91], v[110:113], v[126:129], v[88:91]
	v_addc_co_u32_e32 v179, vcc, 0, v163, vcc
	v_add_co_u32_e32 v180, vcc, s88, v162
	s_waitcnt lgkmcnt(3)
	v_mfma_f32_16x16x32_bf16 v[84:87], v[110:113], v[134:137], v[84:87]
	v_addc_co_u32_e32 v181, vcc, 0, v163, vcc
	v_add_co_u32_e32 v208, vcc, s89, v162
	s_waitcnt lgkmcnt(1)
	v_mfma_f32_16x16x32_bf16 v[80:83], v[110:113], v[142:145], v[80:83]
	ds_read_b128 v[110:113], v102 offset:2304
	ds_read_b128 v[150:153], v102 offset:2368
	v_lshl_add_u64 v[176:177], s[12:13], 0, v[104:105]
	v_addc_co_u32_e32 v209, vcc, 0, v163, vcc
	s_waitcnt lgkmcnt(1)
	v_mfma_f32_16x16x32_bf16 v[76:79], v[110:113], v[114:117], v[76:79]
	v_add_co_u32_e32 v210, vcc, s85, v176
	s_add_i32 s9, s9, 2
	v_mfma_f32_16x16x32_bf16 v[72:75], v[110:113], v[126:129], v[72:75]
	v_addc_co_u32_e32 v211, vcc, 0, v177, vcc
	v_add_co_u32_e32 v212, vcc, s88, v176
	v_mfma_f32_16x16x32_bf16 v[68:71], v[110:113], v[134:137], v[68:71]
	s_nop 0
	v_addc_co_u32_e32 v213, vcc, 0, v177, vcc
	v_add_co_u32_e32 v214, vcc, s89, v176
	v_mfma_f32_16x16x32_bf16 v[64:67], v[110:113], v[142:145], v[64:67]
	ds_read_b128 v[110:113], v102 offset:4608
	ds_read_b128 v[154:157], v102 offset:4672
	v_addc_co_u32_e32 v215, vcc, 0, v177, vcc
	s_waitcnt lgkmcnt(1)
	v_mfma_f32_16x16x32_bf16 v[60:63], v[110:113], v[114:117], v[60:63]
	s_add_u32 s12, s12, 0x100
	s_addc_u32 s13, s13, 0
	s_add_u32 s10, s10, 0x100
	v_mfma_f32_16x16x32_bf16 v[56:59], v[110:113], v[126:129], v[56:59]
	s_addc_u32 s11, s11, 0
	s_cmp_lt_u32 s9, 12
	v_mfma_f32_16x16x32_bf16 v[52:55], v[110:113], v[134:137], v[52:55]
	v_mfma_f32_16x16x32_bf16 v[48:51], v[110:113], v[142:145], v[48:51]
	ds_read_b128 v[110:113], v102 offset:6912
	ds_read_b128 v[158:161], v102 offset:6976
	s_waitcnt vmcnt(7)
	ds_write_b128 v107, v[4:7] offset:36864
	s_waitcnt vmcnt(6)
	ds_write_b128 v107, v[24:27] offset:41472
	s_waitcnt vmcnt(5)
	ds_write_b128 v107, v[8:11] offset:46080
	s_waitcnt vmcnt(4)
	ds_write_b128 v107, v[12:15] offset:50688
	s_waitcnt vmcnt(3)
	ds_write_b128 v107, v[28:31] offset:55296
	s_waitcnt lgkmcnt(6)
	v_mfma_f32_16x16x32_bf16 v[44:47], v[110:113], v[114:117], v[44:47]
	s_waitcnt vmcnt(2)
	ds_write_b128 v107, v[16:19] offset:59904
	s_waitcnt vmcnt(1)
	ds_write_b128 v107, v[20:23] offset:64512
	s_waitcnt vmcnt(0)
	ds_write_b128 v108, v[32:35] offset:32256
	global_load_dwordx4 v[114:117], v[176:177], off offset:256
	v_mfma_f32_16x16x32_bf16 v[40:43], v[110:113], v[126:129], v[40:43]
	v_mfma_f32_16x16x32_bf16 v[92:95], v[110:113], v[134:137], v[92:95]
	v_mfma_f32_16x16x32_bf16 v[36:39], v[110:113], v[142:145], v[36:39]
	global_load_dwordx4 v[110:113], v[162:163], off offset:256
	v_mfma_f32_16x16x32_bf16 v[96:99], v[118:121], v[122:125], v[96:99]
	v_mfma_f32_16x16x32_bf16 v[88:91], v[118:121], v[130:133], v[88:91]
	v_mfma_f32_16x16x32_bf16 v[4:7], v[118:121], v[138:141], v[84:87]
	v_mfma_f32_16x16x32_bf16 v[8:11], v[118:121], v[146:149], v[80:83]
	global_load_dwordx4 v[118:121], v[178:179], off offset:256
	global_load_dwordx4 v[126:129], v[180:181], off offset:256
	global_load_dwordx4 v[134:137], v[208:209], off offset:256
	v_mfma_f32_16x16x32_bf16 v[12:15], v[150:153], v[122:125], v[76:79]
	v_mfma_f32_16x16x32_bf16 v[16:19], v[150:153], v[130:133], v[72:75]
	v_mfma_f32_16x16x32_bf16 v[20:23], v[150:153], v[138:141], v[68:71]
	v_mfma_f32_16x16x32_bf16 v[24:27], v[150:153], v[146:149], v[64:67]
	v_mfma_f32_16x16x32_bf16 v[28:31], v[154:157], v[122:125], v[60:63]
	s_waitcnt lgkmcnt(8)
	v_mfma_f32_16x16x32_bf16 v[44:47], v[158:161], v[122:125], v[44:47]
	global_load_dwordx4 v[122:125], v[210:211], off offset:256
	global_load_dwordx4 v[142:145], v[212:213], off offset:256
	global_load_dwordx4 v[150:153], v[214:215], off offset:256
	s_waitcnt lgkmcnt(0)
	s_barrier
	ds_read_b128 v[60:63], v102 offset:36864
	v_mfma_f32_16x16x32_bf16 v[32:35], v[154:157], v[130:133], v[56:59]
	v_mfma_f32_16x16x32_bf16 v[40:43], v[158:161], v[130:133], v[40:43]
	v_mfma_f32_16x16x32_bf16 v[56:59], v[158:161], v[138:141], v[92:95]
	ds_read_b128 v[64:67], v103 offset:55296
	ds_read_b128 v[68:71], v102 offset:36928
	s_nop 0
	ds_read_b128 v[92:95], v103 offset:55360
	ds_read_b128 v[76:79], v103 offset:57600
	ds_read_b128 v[130:133], v103 offset:57664
	v_mfma_f32_16x16x32_bf16 v[52:55], v[154:157], v[138:141], v[52:55]
	ds_read_b128 v[84:87], v103 offset:59904
	ds_read_b128 v[138:141], v103 offset:59968
	v_mfma_f32_16x16x32_bf16 v[48:51], v[154:157], v[146:149], v[48:51]
	v_mfma_f32_16x16x32_bf16 v[36:39], v[158:161], v[146:149], v[36:39]
	s_waitcnt lgkmcnt(3)
	v_mfma_f32_16x16x32_bf16 v[80:83], v[60:63], v[76:79], v[88:91]
	s_nop 2
	ds_read_b128 v[88:91], v103 offset:62208
	ds_read_b128 v[146:149], v103 offset:62272
	v_mfma_f32_16x16x32_bf16 v[72:75], v[60:63], v[64:67], v[96:99]
	s_waitcnt lgkmcnt(3)
	v_mfma_f32_16x16x32_bf16 v[4:7], v[60:63], v[84:87], v[4:7]
	s_waitcnt lgkmcnt(1)
	v_mfma_f32_16x16x32_bf16 v[8:11], v[60:63], v[88:91], v[8:11]
	ds_read_b128 v[60:63], v102 offset:39168
	ds_read_b128 v[154:157], v102 offset:39232
	s_waitcnt lgkmcnt(1)
	v_mfma_f32_16x16x32_bf16 v[12:15], v[60:63], v[64:67], v[12:15]
	v_mfma_f32_16x16x32_bf16 v[16:19], v[60:63], v[76:79], v[16:19]
	v_mfma_f32_16x16x32_bf16 v[20:23], v[60:63], v[84:87], v[20:23]
	v_mfma_f32_16x16x32_bf16 v[24:27], v[60:63], v[88:91], v[24:27]
	ds_read_b128 v[60:63], v102 offset:41472
	ds_read_b128 v[158:161], v102 offset:41536
	s_waitcnt lgkmcnt(1)
; DI void gemm_kloop(const bf16_t* __restrict__ A, int lda, const bf16_t* __restrict__ B, int ldb, int K, bf16_t* sm,
;                    f32x4 (&acc)[4][4]) {
;     ...
;   __syncthreads();
;   GLOAD(ra0, rb0, 0)
;   GLOAD(ra1, rb1, 64)
;   SSTORE(ra0, rb0, 0)
;   __syncthreads();
;   for (int kt = 0; kt < nk - 2; kt += 2) {
;     GLOAD(ra0, rb0, (kt + 2) << 6)
;     COMPUTE(0)
;     SSTORE(ra1, rb1, 1)
;     __syncthreads();
;     GLOAD(ra1, rb1, (kt + 3) << 6)
;     COMPUTE(1)
;     SSTORE(ra0, rb0, 0)
;     __syncthreads();
;   }
;   COMPUTE(0)
;   SSTORE(ra1, rb1, 1)
;   __syncthreads();
;   COMPUTE(1)
	v_mfma_f32_16x16x32_bf16 v[28:31], v[60:63], v[64:67], v[28:31]
	v_mfma_f32_16x16x32_bf16 v[32:35], v[60:63], v[76:79], v[32:35]
	v_mfma_f32_16x16x32_bf16 v[52:55], v[60:63], v[84:87], v[52:55]
	v_mfma_f32_16x16x32_bf16 v[48:51], v[60:63], v[88:91], v[48:51]
	ds_read_b128 v[60:63], v102 offset:43776
	ds_read_b128 v[168:171], v102 offset:43840
	s_waitcnt lgkmcnt(1)
	v_mfma_f32_16x16x32_bf16 v[44:47], v[60:63], v[64:67], v[44:47]
	v_mfma_f32_16x16x32_bf16 v[40:43], v[60:63], v[76:79], v[40:43]
	v_mfma_f32_16x16x32_bf16 v[172:175], v[60:63], v[84:87], v[56:59]
	v_mfma_f32_16x16x32_bf16 v[36:39], v[60:63], v[88:91], v[36:39]
	v_mfma_f32_16x16x32_bf16 v[96:99], v[68:71], v[92:95], v[72:75]
	v_mfma_f32_16x16x32_bf16 v[88:91], v[68:71], v[130:133], v[80:83]
	v_mfma_f32_16x16x32_bf16 v[84:87], v[68:71], v[138:141], v[4:7]
	v_mfma_f32_16x16x32_bf16 v[80:83], v[68:71], v[146:149], v[8:11]
	s_nop 1
	global_load_dwordx4 v[4:7], v[162:163], off offset:384
	v_mfma_f32_16x16x32_bf16 v[76:79], v[154:157], v[92:95], v[12:15]
	v_mfma_f32_16x16x32_bf16 v[72:75], v[154:157], v[130:133], v[16:19]
	v_mfma_f32_16x16x32_bf16 v[68:71], v[154:157], v[138:141], v[20:23]
	v_mfma_f32_16x16x32_bf16 v[64:67], v[154:157], v[146:149], v[24:27]
	s_nop 2
	global_load_dwordx4 v[24:27], v[178:179], off offset:384
	global_load_dwordx4 v[8:11], v[180:181], off offset:384
	global_load_dwordx4 v[12:15], v[208:209], off offset:384
	v_mfma_f32_16x16x32_bf16 v[60:63], v[158:161], v[92:95], v[28:31]
	s_nop 2
	global_load_dwordx4 v[28:31], v[176:177], off offset:384
	global_load_dwordx4 v[16:19], v[210:211], off offset:384
	global_load_dwordx4 v[20:23], v[212:213], off offset:384
	v_mfma_f32_16x16x32_bf16 v[56:59], v[158:161], v[130:133], v[32:35]
	s_nop 2
	global_load_dwordx4 v[32:35], v[214:215], off offset:384
	v_mfma_f32_16x16x32_bf16 v[52:55], v[158:161], v[138:141], v[52:55]
	s_waitcnt vmcnt(14)
	ds_write_b128 v107, v[110:113]
	ds_write_b128 v107, v[114:117] offset:18432
	s_waitcnt vmcnt(13)
	ds_write_b128 v107, v[118:121] offset:4608
	s_waitcnt vmcnt(12)
	ds_write_b128 v107, v[126:129] offset:9216
	s_waitcnt vmcnt(11)
	ds_write_b128 v107, v[134:137] offset:13824
	s_waitcnt vmcnt(10)
	ds_write_b128 v107, v[122:125] offset:23040
	s_waitcnt vmcnt(9)
	ds_write_b128 v107, v[142:145] offset:27648
	s_waitcnt vmcnt(8)
	ds_write_b128 v107, v[150:153] offset:32256
	s_waitcnt lgkmcnt(0)
	s_barrier
	ds_read_b128 v[110:113], v102
	ds_read_b128 v[114:117], v103 offset:18432
	ds_read_b128 v[118:121], v102 offset:64
	ds_read_b128 v[122:125], v103 offset:18496
	ds_read_b128 v[126:129], v103 offset:20736
	ds_read_b128 v[134:137], v103 offset:23040
	ds_read_b128 v[142:145], v103 offset:25344
	v_mfma_f32_16x16x32_bf16 v[48:51], v[158:161], v[146:149], v[48:51]
	v_mfma_f32_16x16x32_bf16 v[44:47], v[168:171], v[92:95], v[44:47]
	v_mfma_f32_16x16x32_bf16 v[40:43], v[168:171], v[130:133], v[40:43]
	v_mfma_f32_16x16x32_bf16 v[92:95], v[168:171], v[138:141], v[172:175]
	v_mfma_f32_16x16x32_bf16 v[36:39], v[168:171], v[146:149], v[36:39]
	s_cbranch_scc1 .LBB0_1701
	ds_read_b128 v[110:113], v102
	ds_read_b128 v[114:117], v103 offset:18432
	ds_read_b128 v[118:121], v103 offset:20736
	ds_read_b128 v[122:125], v103 offset:23040
	ds_read_b128 v[126:129], v103 offset:25344
	s_movk_i32 s9, 0x5ff
	s_waitcnt lgkmcnt(3)
	v_mfma_f32_16x16x32_bf16 v[96:99], v[110:113], v[114:117], v[96:99]
	s_waitcnt lgkmcnt(2)
	v_mfma_f32_16x16x32_bf16 v[88:91], v[110:113], v[118:121], v[88:91]
	s_waitcnt lgkmcnt(1)
	v_mfma_f32_16x16x32_bf16 v[84:87], v[110:113], v[122:125], v[84:87]
	s_waitcnt lgkmcnt(0)
	v_mfma_f32_16x16x32_bf16 v[80:83], v[110:113], v[126:129], v[80:83]
	ds_read_b128 v[110:113], v102 offset:2304
	s_waitcnt lgkmcnt(0)
	v_mfma_f32_16x16x32_bf16 v[76:79], v[110:113], v[114:117], v[76:79]
	v_mfma_f32_16x16x32_bf16 v[72:75], v[110:113], v[118:121], v[72:75]
	v_mfma_f32_16x16x32_bf16 v[68:71], v[110:113], v[122:125], v[68:71]
	v_mfma_f32_16x16x32_bf16 v[64:67], v[110:113], v[126:129], v[64:67]
	ds_read_b128 v[110:113], v102 offset:4608
	s_waitcnt lgkmcnt(0)
	v_mfma_f32_16x16x32_bf16 v[60:63], v[110:113], v[114:117], v[60:63]
	v_mfma_f32_16x16x32_bf16 v[56:59], v[110:113], v[118:121], v[56:59]
	v_mfma_f32_16x16x32_bf16 v[52:55], v[110:113], v[122:125], v[52:55]
	v_mfma_f32_16x16x32_bf16 v[48:51], v[110:113], v[126:129], v[48:51]
	ds_read_b128 v[110:113], v102 offset:6912
	s_waitcnt lgkmcnt(0)
	v_mfma_f32_16x16x32_bf16 v[44:47], v[110:113], v[114:117], v[44:47]
	ds_read_b128 v[114:117], v102 offset:64
	v_mfma_f32_16x16x32_bf16 v[40:43], v[110:113], v[118:121], v[40:43]
	ds_read_b128 v[118:121], v103 offset:20800
	v_mfma_f32_16x16x32_bf16 v[92:95], v[110:113], v[122:125], v[92:95]
	ds_read_b128 v[122:125], v103 offset:23104
	v_mfma_f32_16x16x32_bf16 v[36:39], v[110:113], v[126:129], v[36:39]
	ds_read_b128 v[110:113], v103 offset:18496
	ds_read_b128 v[126:129], v103 offset:25408
	s_waitcnt lgkmcnt(1)
	v_mfma_f32_16x16x32_bf16 v[96:99], v[114:117], v[110:113], v[96:99]
	v_mfma_f32_16x16x32_bf16 v[88:91], v[114:117], v[118:121], v[88:91]
	v_mfma_f32_16x16x32_bf16 v[84:87], v[114:117], v[122:125], v[84:87]
	s_waitcnt lgkmcnt(0)
	v_mfma_f32_16x16x32_bf16 v[80:83], v[114:117], v[126:129], v[80:83]
	ds_read_b128 v[114:117], v102 offset:2368
	s_waitcnt lgkmcnt(0)
	v_mfma_f32_16x16x32_bf16 v[76:79], v[114:117], v[110:113], v[76:79]
	v_mfma_f32_16x16x32_bf16 v[130:133], v[114:117], v[118:121], v[72:75]
	v_mfma_f32_16x16x32_bf16 v[134:137], v[114:117], v[122:125], v[68:71]
	v_mfma_f32_16x16x32_bf16 v[64:67], v[114:117], v[126:129], v[64:67]
	s_nop 1
	ds_read_b128 v[68:71], v102 offset:4672
	ds_read_b128 v[114:117], v102 offset:6976
	s_waitcnt vmcnt(7)
	ds_write_b128 v107, v[4:7] offset:36864
	s_waitcnt vmcnt(6)
	ds_write_b128 v107, v[24:27] offset:41472
	s_waitcnt vmcnt(5)
	ds_write_b128 v107, v[8:11] offset:46080
	s_waitcnt vmcnt(4)
	ds_write_b128 v107, v[12:15] offset:50688
	s_waitcnt vmcnt(3)
	ds_write_b128 v107, v[28:31] offset:55296
	s_waitcnt vmcnt(2)
	ds_write_b128 v107, v[16:19] offset:59904
	s_waitcnt vmcnt(1)
	ds_write_b128 v107, v[20:23] offset:64512
	s_waitcnt vmcnt(0)
	ds_write_b128 v108, v[32:35] offset:32256
	s_waitcnt lgkmcnt(0)
	s_barrier
; DI bf16_t f2bf(float f) { return (bf16_t)(pack2(f, f) & 0xFFFFu); }
; DI float sigmoidf_(float x) { return __builtin_amdgcn_rcpf(1.f + __expf(-x)); }
; DI void gemm_kloop(const bf16_t* __restrict__ A, int lda, const bf16_t* __restrict__ B, int ldb, int K, bf16_t* sm,
;                    f32x4 (&acc)[4][4]) {
;     ...
;   COMPUTE(1)
;   __syncthreads();
; DI void gemm2_phase(const Params& p, int l, char* smem, const bool dry = false) {
;     ...
;     } else {
; #pragma unroll
;       for (int i = 0; i < 4; i++)
; #pragma unroll
;         for (int r = 0; r < 4; r++) {
;           const int tok = mt * 128 + wm * 64 + i * 16 + g4 * 4 + r;
; #pragma unroll
;           for (int jn = 0; jn < 4; jn++)
;             p.G[(size_t)tok * 3072 + nb - 1536 + jn * 16 + cl] = f2bf(sigmoidf_(acc[i][jn][r]));
;         }
	ds_read_b128 v[16:19], v102 offset:36864
	ds_read_b128 v[20:23], v103 offset:55296
	ds_read_b128 v[28:31], v103 offset:57600
	ds_read_b128 v[12:15], v103 offset:59904
	ds_read_b128 v[8:11], v103 offset:62208
	v_mfma_f32_16x16x32_bf16 v[72:75], v[114:117], v[118:121], v[40:43]
	v_mfma_f32_16x16x32_bf16 v[4:7], v[114:117], v[126:129], v[36:39]
	s_waitcnt lgkmcnt(3)
	v_mfma_f32_16x16x32_bf16 v[24:27], v[16:19], v[20:23], v[96:99]
	s_waitcnt lgkmcnt(2)
	v_mfma_f32_16x16x32_bf16 v[32:35], v[16:19], v[28:31], v[88:91]
	s_waitcnt lgkmcnt(1)
	v_mfma_f32_16x16x32_bf16 v[36:39], v[16:19], v[12:15], v[84:87]
	s_waitcnt lgkmcnt(0)
	v_mfma_f32_16x16x32_bf16 v[40:43], v[16:19], v[8:11], v[80:83]
	ds_read_b128 v[16:19], v102 offset:39168
	v_mfma_f32_16x16x32_bf16 v[60:63], v[68:71], v[110:113], v[60:63]
	s_nop 0
	v_or_b32_e32 v80, s17, v101
	v_cmp_lt_i32_e32 vcc, s9, v80
	v_mfma_f32_16x16x32_bf16 v[56:59], v[68:71], v[118:121], v[56:59]
	v_mfma_f32_16x16x32_bf16 v[52:55], v[68:71], v[122:125], v[52:55]
	v_mfma_f32_16x16x32_bf16 v[48:51], v[68:71], v[126:129], v[48:51]
	v_mfma_f32_16x16x32_bf16 v[44:47], v[114:117], v[110:113], v[44:47]
	v_mfma_f32_16x16x32_bf16 v[68:71], v[114:117], v[122:125], v[92:95]
	s_waitcnt lgkmcnt(0)
	v_mfma_f32_16x16x32_bf16 v[88:91], v[16:19], v[20:23], v[76:79]
	v_mfma_f32_16x16x32_bf16 v[92:95], v[16:19], v[28:31], v[130:133]
	s_nop 1
	v_lshl_add_u32 v78, s8, 7, v106
	v_lshlrev_b32_e32 v76, 1, v100
	v_mfma_f32_16x16x32_bf16 v[96:99], v[16:19], v[12:15], v[134:137]
	v_mfma_f32_16x16x32_bf16 v[108:111], v[16:19], v[8:11], v[64:67]
	ds_read_b128 v[16:19], v102 offset:43776
	s_nop 1
	ds_read_b128 v[64:67], v102 offset:41472
	ds_read_b128 v[120:123], v102 offset:36928
	ds_read_b128 v[154:157], v103 offset:55360
	ds_read_b128 v[124:127], v102 offset:39232
	ds_read_b128 v[168:171], v103 offset:57664
	ds_read_b128 v[172:175], v102 offset:41536
	ds_read_b128 v[176:179], v103 offset:59968
	ds_read_b128 v[212:215], v102 offset:43840
	ds_read_b128 v[102:105], v103 offset:62272
	s_waitcnt lgkmcnt(8)
	v_mfma_f32_16x16x32_bf16 v[112:115], v[64:67], v[20:23], v[60:63]
	s_waitcnt lgkmcnt(0)
	s_barrier
	v_mfma_f32_16x16x32_bf16 v[116:119], v[64:67], v[28:31], v[56:59]
	v_mfma_f32_16x16x32_bf16 v[158:161], v[64:67], v[12:15], v[52:55]
	v_mfma_f32_16x16x32_bf16 v[208:211], v[64:67], v[8:11], v[48:51]
	v_mfma_f32_16x16x32_bf16 v[216:219], v[16:19], v[20:23], v[44:47]
	v_mfma_f32_16x16x32_bf16 v[72:75], v[16:19], v[28:31], v[72:75]
	v_mfma_f32_16x16x32_bf16 v[68:71], v[16:19], v[12:15], v[68:71]
	v_mfma_f32_16x16x32_bf16 v[4:7], v[16:19], v[8:11], v[4:7]
	v_mfma_f32_16x16x32_bf16 v[64:67], v[120:123], v[154:157], v[24:27]
	v_mfma_f32_16x16x32_bf16 v[60:63], v[120:123], v[168:171], v[32:35]
	v_mfma_f32_16x16x32_bf16 v[56:59], v[120:123], v[176:179], v[36:39]
	s_nop 5
	v_mul_f32_e32 v86, 0xbfb8aa3b, v64
	v_mul_f32_e32 v85, 0xbfb8aa3b, v60
	v_mul_f32_e32 v82, 0xbfb8aa3b, v65
	v_mfma_f32_16x16x32_bf16 v[52:55], v[120:123], v[102:105], v[40:43]
	v_mul_f32_e32 v153, 0xbfb8aa3b, v61
	v_mul_f32_e32 v84, 0xbfb8aa3b, v56
	v_mul_f32_e32 v152, 0xbfb8aa3b, v57
	v_mfma_f32_16x16x32_bf16 v[48:51], v[124:127], v[154:157], v[88:91]
	v_mul_f32_e32 v150, 0xbfb8aa3b, v66
	s_nop 2
	v_mul_f32_e32 v83, 0xbfb8aa3b, v52
	v_mul_f32_e32 v151, 0xbfb8aa3b, v53
	v_mfma_f32_16x16x32_bf16 v[44:47], v[124:127], v[168:171], v[92:95]
	v_mul_f32_e32 v149, 0xbfb8aa3b, v62
	v_mul_f32_e32 v148, 0xbfb8aa3b, v58
	v_mul_f32_e32 v147, 0xbfb8aa3b, v54
	v_mfma_f32_16x16x32_bf16 v[40:43], v[124:127], v[176:179], v[96:99]
	v_mul_f32_e32 v146, 0xbfb8aa3b, v67
	v_mul_f32_e32 v145, 0xbfb8aa3b, v63
	v_mul_f32_e32 v144, 0xbfb8aa3b, v59
	v_mfma_f32_16x16x32_bf16 v[36:39], v[124:127], v[102:105], v[108:111]
	v_mul_f32_e32 v143, 0xbfb8aa3b, v55
	v_mul_f32_e32 v142, 0xbfb8aa3b, v48
	v_mul_f32_e32 v141, 0xbfb8aa3b, v44
	v_mfma_f32_16x16x32_bf16 v[32:35], v[172:175], v[154:157], v[112:115]
	v_mul_f32_e32 v140, 0xbfb8aa3b, v40
	s_nop 2
	v_mul_f32_e32 v139, 0xbfb8aa3b, v36
	v_mul_f32_e32 v138, 0xbfb8aa3b, v49
	v_mfma_f32_16x16x32_bf16 v[28:31], v[172:175], v[168:171], v[116:119]
	v_mul_f32_e32 v137, 0xbfb8aa3b, v45
	v_mul_f32_e32 v136, 0xbfb8aa3b, v41
	v_mul_f32_e32 v135, 0xbfb8aa3b, v37
	v_mfma_f32_16x16x32_bf16 v[24:27], v[172:175], v[176:179], v[158:161]
	v_mul_f32_e32 v134, 0xbfb8aa3b, v50
	v_mul_f32_e32 v133, 0xbfb8aa3b, v46
	v_mul_f32_e32 v132, 0xbfb8aa3b, v42
	v_mfma_f32_16x16x32_bf16 v[20:23], v[172:175], v[102:105], v[208:211]
	v_mul_f32_e32 v131, 0xbfb8aa3b, v38
	v_mul_f32_e32 v130, 0xbfb8aa3b, v51
	v_mul_f32_e32 v129, 0xbfb8aa3b, v47
	v_mfma_f32_16x16x32_bf16 v[16:19], v[212:215], v[154:157], v[216:219]
	v_mul_f32_e32 v128, 0xbfb8aa3b, v43
	v_mul_f32_e32 v127, 0xbfb8aa3b, v39
	v_mul_f32_e32 v126, 0xbfb8aa3b, v32
	v_mfma_f32_16x16x32_bf16 v[12:15], v[212:215], v[168:171], v[72:75]
	v_mul_f32_e32 v125, 0xbfb8aa3b, v28
	v_mul_f32_e32 v124, 0xbfb8aa3b, v24
	v_mul_f32_e32 v123, 0xbfb8aa3b, v20
	v_mfma_f32_16x16x32_bf16 v[8:11], v[212:215], v[176:179], v[68:71]
	v_mul_f32_e32 v122, 0xbfb8aa3b, v33
	v_mul_f32_e32 v121, 0xbfb8aa3b, v29
	v_mul_f32_e32 v120, 0xbfb8aa3b, v25
	v_mfma_f32_16x16x32_bf16 v[4:7], v[212:215], v[102:105], v[4:7]
	v_mul_f32_e32 v119, 0xbfb8aa3b, v21
	v_mul_f32_e32 v118, 0xbfb8aa3b, v34
	v_mul_f32_e32 v117, 0xbfb8aa3b, v30
	v_mul_f32_e32 v116, 0xbfb8aa3b, v26
	v_mul_f32_e32 v115, 0xbfb8aa3b, v22
	v_mul_f32_e32 v114, 0xbfb8aa3b, v35
	v_mul_f32_e32 v113, 0xbfb8aa3b, v31
	v_mul_f32_e32 v112, 0xbfb8aa3b, v27
	v_mul_f32_e32 v111, 0xbfb8aa3b, v23
	v_mul_f32_e32 v110, 0xbfb8aa3b, v16
	v_mul_f32_e32 v109, 0xbfb8aa3b, v12
	v_mul_f32_e32 v108, 0xbfb8aa3b, v8
	v_mul_f32_e32 v107, 0xbfb8aa3b, v4
	v_mul_f32_e32 v105, 0xbfb8aa3b, v17
	v_mul_f32_e32 v104, 0xbfb8aa3b, v13
	v_mul_f32_e32 v103, 0xbfb8aa3b, v9
	v_mul_f32_e32 v102, 0xbfb8aa3b, v5
	v_mul_f32_e32 v99, 0xbfb8aa3b, v18
	v_mul_f32_e32 v98, 0xbfb8aa3b, v14
	v_mul_f32_e32 v97, 0xbfb8aa3b, v10
	v_mul_f32_e32 v96, 0xbfb8aa3b, v6
	v_mul_f32_e32 v95, 0xbfb8aa3b, v19
	v_mul_f32_e32 v94, 0xbfb8aa3b, v15
	v_mul_f32_e32 v93, 0xbfb8aa3b, v11
	v_mul_f32_e32 v92, 0xbfb8aa3b, v7
	s_and_saveexec_b64 s[8:9], vcc
	s_xor_b64 s[8:9], exec, s[8:9]
	s_cbranch_execz .LBB0_1704
; DI bf16_t f2bf(float f) { return (bf16_t)(pack2(f, f) & 0xFFFFu); }
; DI float sigmoidf_(float x) { return __builtin_amdgcn_rcpf(1.f + __expf(-x)); }
; DI void gemm2_phase(const Params& p, int l, char* smem, const bool dry = false) {
;     ...
;     } else {
; #pragma unroll
;       for (int i = 0; i < 4; i++)
; #pragma unroll
;         for (int r = 0; r < 4; r++) {
;           const int tok = mt * 128 + wm * 64 + i * 16 + g4 * 4 + r;
; #pragma unroll
;           for (int jn = 0; jn < 4; jn++)
;             p.G[(size_t)tok * 3072 + nb - 1536 + jn * 16 + cl] = f2bf(sigmoidf_(acc[i][jn][r]));
;         }
	v_exp_f32_e32 v8, v86
	v_exp_f32_e32 v9, v85
	s_load_dwordx2 s[10:11], s[0:1], 0x160
	v_mov_b32_e32 v81, v164
	v_add_f32_e32 v8, 1.0, v8
	v_rcp_f32_e32 v8, v8
	v_add_f32_e32 v9, 1.0, v9
	v_rcp_f32_e32 v9, v9
	v_exp_f32_e32 v10, v84
	s_waitcnt lgkmcnt(0)
	v_lshl_add_u64 v[4:5], v[80:81], 1, s[10:11]
	s_movk_i32 s12, 0x1800
	v_mov_b32_e32 v77, v164
	v_mad_i64_i32 v[6:7], s[10:11], v78, s12, v[4:5]
	v_lshl_add_u64 v[6:7], v[6:7], 0, v[76:77]
	v_cvt_pk_bf16_f32 v8, v8, s0
	global_store_short v[6:7], v8, off offset:-3072
	v_cvt_pk_bf16_f32 v8, v9, s0
	v_exp_f32_e32 v9, v83
	v_add_f32_e32 v10, 1.0, v10
	v_rcp_f32_e32 v10, v10
	global_store_short v[6:7], v8, off offset:-3040
	v_add_f32_e32 v8, 1.0, v9
	v_rcp_f32_e32 v8, v8
	v_cvt_pk_bf16_f32 v9, v10, s0
	global_store_short v[6:7], v9, off offset:-3008
	v_exp_f32_e32 v9, v82
	v_cvt_pk_bf16_f32 v8, v8, s0
	global_store_short v[6:7], v8, off offset:-2976
	v_or_b32_e32 v6, 1, v78
	v_add_f32_e32 v7, 1.0, v9
	v_rcp_f32_e32 v8, v7
	v_mad_i64_i32 v[6:7], s[10:11], v6, s12, v[4:5]
	v_lshl_add_u64 v[6:7], v[6:7], 0, v[76:77]
	v_cvt_pk_bf16_f32 v8, v8, s0
	v_exp_f32_e32 v9, v153
	global_store_short v[6:7], v8, off offset:-3072
	v_exp_f32_e32 v8, v151
	v_exp_f32_e32 v10, v152
	v_add_f32_e32 v9, 1.0, v9
	v_rcp_f32_e32 v9, v9
	v_add_f32_e32 v8, 1.0, v8
	v_add_f32_e32 v10, 1.0, v10
	v_rcp_f32_e32 v8, v8
	v_rcp_f32_e32 v10, v10
	v_cvt_pk_bf16_f32 v9, v9, s0
	global_store_short v[6:7], v9, off offset:-3040
	v_cvt_pk_bf16_f32 v8, v8, s0
	v_cvt_pk_bf16_f32 v9, v10, s0
	global_store_short v[6:7], v8, off offset:-2976
	v_exp_f32_e32 v8, v150
	global_store_short v[6:7], v9, off offset:-3008
	v_exp_f32_e32 v9, v149
	v_exp_f32_e32 v10, v148
	v_add_f32_e32 v8, 1.0, v8
	v_rcp_f32_e32 v8, v8
	v_add_f32_e32 v9, 1.0, v9
	v_rcp_f32_e32 v9, v9
	v_or_b32_e32 v6, 2, v78
	v_mad_i64_i32 v[6:7], s[10:11], v6, s12, v[4:5]
	v_lshl_add_u64 v[6:7], v[6:7], 0, v[76:77]
	v_cvt_pk_bf16_f32 v8, v8, s0
	global_store_short v[6:7], v8, off offset:-3072
	v_cvt_pk_bf16_f32 v8, v9, s0
	v_exp_f32_e32 v9, v147
	v_add_f32_e32 v10, 1.0, v10
	v_rcp_f32_e32 v10, v10
	global_store_short v[6:7], v8, off offset:-3040
	v_add_f32_e32 v8, 1.0, v9
	v_rcp_f32_e32 v8, v8
	v_cvt_pk_bf16_f32 v9, v10, s0
	global_store_short v[6:7], v9, off offset:-3008
	v_exp_f32_e32 v9, v146
	v_cvt_pk_bf16_f32 v8, v8, s0
	global_store_short v[6:7], v8, off offset:-2976
	v_or_b32_e32 v6, 3, v78
	v_add_f32_e32 v7, 1.0, v9
	v_rcp_f32_e32 v8, v7
	v_mad_i64_i32 v[6:7], s[10:11], v6, s12, v[4:5]
	v_lshl_add_u64 v[6:7], v[6:7], 0, v[76:77]
	v_cvt_pk_bf16_f32 v8, v8, s0
	v_exp_f32_e32 v9, v145
	global_store_short v[6:7], v8, off offset:-3072
	v_exp_f32_e32 v8, v143
	v_exp_f32_e32 v10, v144
	v_add_f32_e32 v9, 1.0, v9
	v_rcp_f32_e32 v9, v9
	v_add_f32_e32 v8, 1.0, v8
	v_add_f32_e32 v10, 1.0, v10
	v_rcp_f32_e32 v8, v8
	v_rcp_f32_e32 v10, v10
	v_cvt_pk_bf16_f32 v9, v9, s0
	global_store_short v[6:7], v9, off offset:-3040
	v_cvt_pk_bf16_f32 v8, v8, s0
	v_cvt_pk_bf16_f32 v9, v10, s0
	global_store_short v[6:7], v8, off offset:-2976
	v_exp_f32_e32 v8, v142
	global_store_short v[6:7], v9, off offset:-3008
	v_exp_f32_e32 v9, v141
	v_exp_f32_e32 v10, v140
	v_add_f32_e32 v8, 1.0, v8
	v_rcp_f32_e32 v8, v8
	v_add_f32_e32 v9, 1.0, v9
	v_rcp_f32_e32 v9, v9
	v_or_b32_e32 v6, 16, v78
	v_mad_i64_i32 v[6:7], s[10:11], v6, s12, v[4:5]
	v_lshl_add_u64 v[6:7], v[6:7], 0, v[76:77]
	v_cvt_pk_bf16_f32 v8, v8, s0
	global_store_short v[6:7], v8, off offset:-3072
	v_cvt_pk_bf16_f32 v8, v9, s0
	v_exp_f32_e32 v9, v139
	v_add_f32_e32 v10, 1.0, v10
	v_rcp_f32_e32 v10, v10
	global_store_short v[6:7], v8, off offset:-3040
	v_add_f32_e32 v8, 1.0, v9
	v_rcp_f32_e32 v8, v8
	v_cvt_pk_bf16_f32 v9, v10, s0
	global_store_short v[6:7], v9, off offset:-3008
	v_exp_f32_e32 v9, v138
	v_cvt_pk_bf16_f32 v8, v8, s0
	global_store_short v[6:7], v8, off offset:-2976
	v_or_b32_e32 v6, 17, v78
	v_add_f32_e32 v7, 1.0, v9
	v_rcp_f32_e32 v8, v7
	v_mad_i64_i32 v[6:7], s[10:11], v6, s12, v[4:5]
	v_lshl_add_u64 v[6:7], v[6:7], 0, v[76:77]
	v_cvt_pk_bf16_f32 v8, v8, s0
	v_exp_f32_e32 v9, v137
	global_store_short v[6:7], v8, off offset:-3072
	v_exp_f32_e32 v8, v135
	v_exp_f32_e32 v10, v136
	v_add_f32_e32 v9, 1.0, v9
	v_rcp_f32_e32 v9, v9
	v_add_f32_e32 v8, 1.0, v8
	v_add_f32_e32 v10, 1.0, v10
	v_rcp_f32_e32 v8, v8
	v_rcp_f32_e32 v10, v10
	v_cvt_pk_bf16_f32 v9, v9, s0
	global_store_short v[6:7], v9, off offset:-3040
	v_cvt_pk_bf16_f32 v8, v8, s0
	v_cvt_pk_bf16_f32 v9, v10, s0
	global_store_short v[6:7], v8, off offset:-2976
	v_exp_f32_e32 v8, v134
	global_store_short v[6:7], v9, off offset:-3008
	v_exp_f32_e32 v9, v133
	v_exp_f32_e32 v10, v132
	v_add_f32_e32 v8, 1.0, v8
	v_rcp_f32_e32 v8, v8
	v_add_f32_e32 v9, 1.0, v9
	v_rcp_f32_e32 v9, v9
	v_or_b32_e32 v6, 18, v78
	v_mad_i64_i32 v[6:7], s[10:11], v6, s12, v[4:5]
	v_lshl_add_u64 v[6:7], v[6:7], 0, v[76:77]
	v_cvt_pk_bf16_f32 v8, v8, s0
	global_store_short v[6:7], v8, off offset:-3072
	v_cvt_pk_bf16_f32 v8, v9, s0
	v_exp_f32_e32 v9, v131
	v_add_f32_e32 v10, 1.0, v10
	v_rcp_f32_e32 v10, v10
	global_store_short v[6:7], v8, off offset:-3040
	v_add_f32_e32 v8, 1.0, v9
	v_rcp_f32_e32 v8, v8
	v_cvt_pk_bf16_f32 v9, v10, s0
	global_store_short v[6:7], v9, off offset:-3008
	v_exp_f32_e32 v9, v130
	v_cvt_pk_bf16_f32 v8, v8, s0
	global_store_short v[6:7], v8, off offset:-2976
	v_or_b32_e32 v6, 19, v78
	v_add_f32_e32 v7, 1.0, v9
	v_rcp_f32_e32 v8, v7
	v_mad_i64_i32 v[6:7], s[10:11], v6, s12, v[4:5]
	v_lshl_add_u64 v[6:7], v[6:7], 0, v[76:77]
	v_cvt_pk_bf16_f32 v8, v8, s0
	v_exp_f32_e32 v9, v129
	global_store_short v[6:7], v8, off offset:-3072
	v_exp_f32_e32 v8, v127
	v_exp_f32_e32 v10, v128
	v_add_f32_e32 v9, 1.0, v9
; DI bf16_t f2bf(float f) { return (bf16_t)(pack2(f, f) & 0xFFFFu); }
; DI float sigmoidf_(float x) { return __builtin_amdgcn_rcpf(1.f + __expf(-x)); }
; DI void gemm2_phase(const Params& p, int l, char* smem, const bool dry = false) {
;     ...
;     } else {
; #pragma unroll
;       for (int i = 0; i < 4; i++)
; #pragma unroll
;         for (int r = 0; r < 4; r++) {
;           const int tok = mt * 128 + wm * 64 + i * 16 + g4 * 4 + r;
; #pragma unroll
;           for (int jn = 0; jn < 4; jn++)
;             p.G[(size_t)tok * 3072 + nb - 1536 + jn * 16 + cl] = f2bf(sigmoidf_(acc[i][jn][r]));
;         }
	v_rcp_f32_e32 v9, v9
	v_add_f32_e32 v8, 1.0, v8
	v_add_f32_e32 v10, 1.0, v10
	v_rcp_f32_e32 v8, v8
	v_rcp_f32_e32 v10, v10
	v_cvt_pk_bf16_f32 v9, v9, s0
	global_store_short v[6:7], v9, off offset:-3040
	v_cvt_pk_bf16_f32 v8, v8, s0
	v_cvt_pk_bf16_f32 v9, v10, s0
	global_store_short v[6:7], v8, off offset:-2976
	v_exp_f32_e32 v8, v126
	global_store_short v[6:7], v9, off offset:-3008
	v_exp_f32_e32 v9, v125
	v_exp_f32_e32 v10, v124
	v_add_f32_e32 v8, 1.0, v8
	v_rcp_f32_e32 v8, v8
	v_add_f32_e32 v9, 1.0, v9
	v_rcp_f32_e32 v9, v9
	v_or_b32_e32 v6, 32, v78
	v_mad_i64_i32 v[6:7], s[10:11], v6, s12, v[4:5]
	v_lshl_add_u64 v[6:7], v[6:7], 0, v[76:77]
	v_cvt_pk_bf16_f32 v8, v8, s0
	global_store_short v[6:7], v8, off offset:-3072
	v_cvt_pk_bf16_f32 v8, v9, s0
	v_exp_f32_e32 v9, v123
	v_add_f32_e32 v10, 1.0, v10
	v_rcp_f32_e32 v10, v10
	global_store_short v[6:7], v8, off offset:-3040
	v_add_f32_e32 v8, 1.0, v9
	v_rcp_f32_e32 v8, v8
	v_cvt_pk_bf16_f32 v9, v10, s0
	global_store_short v[6:7], v9, off offset:-3008
	v_exp_f32_e32 v9, v122
	v_cvt_pk_bf16_f32 v8, v8, s0
	global_store_short v[6:7], v8, off offset:-2976
	v_or_b32_e32 v6, 33, v78
	v_add_f32_e32 v7, 1.0, v9
	v_rcp_f32_e32 v8, v7
	v_mad_i64_i32 v[6:7], s[10:11], v6, s12, v[4:5]
	v_lshl_add_u64 v[6:7], v[6:7], 0, v[76:77]
	v_cvt_pk_bf16_f32 v8, v8, s0
	v_exp_f32_e32 v9, v121
	global_store_short v[6:7], v8, off offset:-3072
	v_exp_f32_e32 v8, v119
	v_exp_f32_e32 v10, v120
	v_add_f32_e32 v9, 1.0, v9
	v_rcp_f32_e32 v9, v9
	v_add_f32_e32 v8, 1.0, v8
	v_add_f32_e32 v10, 1.0, v10
	v_rcp_f32_e32 v8, v8
	v_rcp_f32_e32 v10, v10
	v_cvt_pk_bf16_f32 v9, v9, s0
	global_store_short v[6:7], v9, off offset:-3040
	v_cvt_pk_bf16_f32 v8, v8, s0
	v_cvt_pk_bf16_f32 v9, v10, s0
	global_store_short v[6:7], v8, off offset:-2976
	v_exp_f32_e32 v8, v118
	global_store_short v[6:7], v9, off offset:-3008
	v_exp_f32_e32 v9, v117
	v_exp_f32_e32 v10, v116
	v_add_f32_e32 v8, 1.0, v8
	v_rcp_f32_e32 v8, v8
	v_add_f32_e32 v9, 1.0, v9
	v_rcp_f32_e32 v9, v9
	v_or_b32_e32 v6, 34, v78
	v_mad_i64_i32 v[6:7], s[10:11], v6, s12, v[4:5]
	v_lshl_add_u64 v[6:7], v[6:7], 0, v[76:77]
	v_cvt_pk_bf16_f32 v8, v8, s0
	global_store_short v[6:7], v8, off offset:-3072
	v_cvt_pk_bf16_f32 v8, v9, s0
	v_exp_f32_e32 v9, v115
	v_add_f32_e32 v10, 1.0, v10
	v_rcp_f32_e32 v10, v10
	global_store_short v[6:7], v8, off offset:-3040
	v_add_f32_e32 v8, 1.0, v9
	v_rcp_f32_e32 v8, v8
	v_cvt_pk_bf16_f32 v9, v10, s0
	global_store_short v[6:7], v9, off offset:-3008
	v_exp_f32_e32 v9, v114
	v_cvt_pk_bf16_f32 v8, v8, s0
	global_store_short v[6:7], v8, off offset:-2976
	v_or_b32_e32 v6, 35, v78
	v_add_f32_e32 v7, 1.0, v9
	v_rcp_f32_e32 v8, v7
	v_mad_i64_i32 v[6:7], s[10:11], v6, s12, v[4:5]
	v_lshl_add_u64 v[6:7], v[6:7], 0, v[76:77]
	v_cvt_pk_bf16_f32 v8, v8, s0
	v_exp_f32_e32 v9, v113
	global_store_short v[6:7], v8, off offset:-3072
	v_exp_f32_e32 v8, v111
	v_exp_f32_e32 v10, v112
	v_add_f32_e32 v9, 1.0, v9
	v_rcp_f32_e32 v9, v9
	v_add_f32_e32 v8, 1.0, v8
	v_add_f32_e32 v10, 1.0, v10
	v_rcp_f32_e32 v8, v8
	v_rcp_f32_e32 v10, v10
	v_cvt_pk_bf16_f32 v9, v9, s0
	global_store_short v[6:7], v9, off offset:-3040
	v_cvt_pk_bf16_f32 v8, v8, s0
	v_cvt_pk_bf16_f32 v9, v10, s0
	global_store_short v[6:7], v8, off offset:-2976
	v_exp_f32_e32 v8, v110
	global_store_short v[6:7], v9, off offset:-3008
	v_exp_f32_e32 v9, v109
	v_exp_f32_e32 v10, v108
	v_add_f32_e32 v8, 1.0, v8
	v_rcp_f32_e32 v8, v8
	v_add_f32_e32 v9, 1.0, v9
	v_rcp_f32_e32 v9, v9
	v_or_b32_e32 v6, 48, v78
	v_mad_i64_i32 v[6:7], s[10:11], v6, s12, v[4:5]
	v_lshl_add_u64 v[6:7], v[6:7], 0, v[76:77]
	v_cvt_pk_bf16_f32 v8, v8, s0
	global_store_short v[6:7], v8, off offset:-3072
	v_cvt_pk_bf16_f32 v8, v9, s0
	v_exp_f32_e32 v9, v107
	v_add_f32_e32 v10, 1.0, v10
	v_rcp_f32_e32 v10, v10
	global_store_short v[6:7], v8, off offset:-3040
	v_add_f32_e32 v8, 1.0, v9
	v_rcp_f32_e32 v8, v8
	v_cvt_pk_bf16_f32 v9, v10, s0
	global_store_short v[6:7], v9, off offset:-3008
	v_exp_f32_e32 v9, v105
	v_cvt_pk_bf16_f32 v8, v8, s0
	global_store_short v[6:7], v8, off offset:-2976
	v_or_b32_e32 v6, 49, v78
	v_add_f32_e32 v7, 1.0, v9
	v_rcp_f32_e32 v8, v7
	v_mad_i64_i32 v[6:7], s[10:11], v6, s12, v[4:5]
	v_lshl_add_u64 v[6:7], v[6:7], 0, v[76:77]
	v_cvt_pk_bf16_f32 v8, v8, s0
	v_exp_f32_e32 v9, v104
	global_store_short v[6:7], v8, off offset:-3072
	v_exp_f32_e32 v8, v102
	v_exp_f32_e32 v10, v103
	v_add_f32_e32 v9, 1.0, v9
	v_rcp_f32_e32 v9, v9
	v_add_f32_e32 v8, 1.0, v8
	v_add_f32_e32 v10, 1.0, v10
	v_rcp_f32_e32 v8, v8
	v_rcp_f32_e32 v10, v10
	v_cvt_pk_bf16_f32 v9, v9, s0
	global_store_short v[6:7], v9, off offset:-3040
	v_cvt_pk_bf16_f32 v8, v8, s0
	v_cvt_pk_bf16_f32 v9, v10, s0
	global_store_short v[6:7], v8, off offset:-2976
	v_exp_f32_e32 v8, v99
	global_store_short v[6:7], v9, off offset:-3008
	v_exp_f32_e32 v9, v98
	v_exp_f32_e32 v10, v97
	v_add_f32_e32 v8, 1.0, v8
	v_rcp_f32_e32 v8, v8
	v_add_f32_e32 v9, 1.0, v9
	v_rcp_f32_e32 v9, v9
	v_or_b32_e32 v6, 50, v78
	v_mad_i64_i32 v[6:7], s[10:11], v6, s12, v[4:5]
	v_lshl_add_u64 v[6:7], v[6:7], 0, v[76:77]
	v_cvt_pk_bf16_f32 v8, v8, s0
	global_store_short v[6:7], v8, off offset:-3072
	v_cvt_pk_bf16_f32 v8, v9, s0
	v_exp_f32_e32 v9, v96
	v_add_f32_e32 v10, 1.0, v10
	v_rcp_f32_e32 v10, v10
	global_store_short v[6:7], v8, off offset:-3040
	v_add_f32_e32 v8, 1.0, v9
	v_rcp_f32_e32 v8, v8
	v_cvt_pk_bf16_f32 v9, v10, s0
	global_store_short v[6:7], v9, off offset:-3008
	v_exp_f32_e32 v9, v95
	v_cvt_pk_bf16_f32 v8, v8, s0
	global_store_short v[6:7], v8, off offset:-2976
	v_exp_f32_e32 v8, v94
	v_add_f32_e32 v7, 1.0, v9
	v_rcp_f32_e32 v7, v7
	v_or_b32_e32 v6, 51, v78
	v_mad_i64_i32 v[4:5], s[10:11], v6, s12, v[4:5]
	v_lshl_add_u64 v[4:5], v[4:5], 0, v[76:77]
	v_cvt_pk_bf16_f32 v6, v7, s0
	v_add_f32_e32 v7, 1.0, v8
	v_exp_f32_e32 v8, v93
	global_store_short v[4:5], v6, off offset:-3072
	v_exp_f32_e32 v6, v92
	v_rcp_f32_e32 v7, v7
	v_add_f32_e32 v8, 1.0, v8
	v_rcp_f32_e32 v8, v8
	v_add_f32_e32 v6, 1.0, v6
	v_rcp_f32_e32 v6, v6
	v_cvt_pk_bf16_f32 v7, v7, s0
	global_store_short v[4:5], v7, off offset:-3040
	v_cvt_pk_bf16_f32 v7, v8, s0
	v_cvt_pk_bf16_f32 v6, v6, s0
	global_store_short v[4:5], v7, off offset:-3008
	global_store_short v[4:5], v6, off offset:-2976

; DI void gemm_kloop(const bf16_t* __restrict__ A, int lda, const bf16_t* __restrict__ B, int ldb, int K, bf16_t* sm,
;                    f32x4 (&acc)[4][4]) {
;     ...
;   __syncthreads();
;   GLOAD(ra0, rb0, 0)
;   GLOAD(ra1, rb1, 64)
;   SSTORE(ra0, rb0, 0)
;   __syncthreads();
; DI void out_phase(const Params& p, int l, char* smem, const bool dry = false) {
;     ...
;   for (int e = slot;; e += slots) {
;     int mt, nt;
;     if (!xcd_tile(e, 8, mt, nt)) break;
;     f32x4 acc[4][4];
;     zero_acc(acc);
;     gemm_kloop(p.merged + (size_t)mt * 128 * DM, DM, p.Wout + ((size_t)l * DM + nt * 128) * DM, DM, DM, sm, acc);
.LBB0_1738:
	v_mov_b64_e32 v[226:227], s[58:59]
	v_mov_b64_e32 v[228:229], s[86:87]
	v_mov_b64_e32 v[230:231], s[0:1]
	global_load_dwordx2 v[220:221], v[226:227], off
	global_load_dwordx2 v[222:223], v[228:229], off
	global_load_dwordx2 v[224:225], v[230:231], off
	s_cmpk_lt_u32 s17, 0x48
	s_cselect_b32 s4, 0, 0xffffffb8
	s_cselect_b32 s5, 0, 9
	s_add_i32 s19, s4, s17
	s_mul_i32 s4, s19, 0xe39
	s_lshr_b32 s10, s4, 31
	s_ashr_i32 s4, s4, 18
	s_add_i32 s20, s4, s10
	s_mul_i32 s4, s20, 0xffffffb8
	s_add_i32 s12, s4, s19
	s_bfe_u32 s4, s12, 0x3001c
	s_add_i32 s4, s12, s4
	s_sext_i32_i16 s4, s4
	s_ashr_i32 s13, s4, 3
	v_readlane_b32 s4, v254, 19
	s_add_i32 s4, s5, s4
	s_add_i32 s4, s4, s13
	s_ashr_i32 s5, s4, 31
	s_lshl_b64 s[10:11], s[4:5], 18
	v_mov_b32_e32 v7, v182
	s_add_u32 s10, s6, s10
	s_addc_u32 s11, s7, s11
	v_lshlrev_b32_e32 v4, 3, v7
	s_lshl_b32 s5, s20, 10
	s_lshl_b32 s12, s12, 7
	v_ashrrev_i32_e32 v14, 3, v7
	v_and_b32_e32 v15, 56, v4
	s_add_i32 s12, s12, s5
	s_lshl_b32 s5, s13, 10
	v_lshl_or_b32 v4, v14, 10, v15
	v_mov_b32_e32 v5, v164
	s_sub_i32 s18, s12, s5
	v_lshlrev_b64 v[102:103], 1, v[4:5]
	s_ashr_i32 s13, s18, 31
	v_lshl_add_u64 v[4:5], s[10:11], 0, v[102:103]
	s_add_u32 s12, s18, s14
	v_add_co_u32_e32 v8, vcc, s85, v4
	s_addc_u32 s13, s13, 0
	s_nop 0
	v_addc_co_u32_e32 v9, vcc, 0, v5, vcc
	s_lshl_b64 s[12:13], s[12:13], 11
	v_add_co_u32_e32 v10, vcc, s88, v4
	s_add_u32 s12, s8, s12
	s_nop 0
	v_addc_co_u32_e32 v11, vcc, 0, v5, vcc
	s_addc_u32 s13, s9, s13
	v_add_co_u32_e32 v12, vcc, s89, v4
	v_lshl_add_u64 v[20:21], s[12:13], 0, v[102:103]
	s_nop 0
	v_addc_co_u32_e32 v13, vcc, 0, v5, vcc
	v_add_co_u32_e32 v22, vcc, s85, v20
	v_and_b32_e32 v16, 15, v7
	s_nop 0
	v_addc_co_u32_e32 v23, vcc, 0, v21, vcc
	v_add_co_u32_e32 v24, vcc, s88, v20
	v_lshrrev_b32_e32 v17, 1, v7
	s_nop 0
	v_addc_co_u32_e32 v25, vcc, 0, v21, vcc
	v_and_b32_e32 v6, 48, v7
	v_and_b32_e32 v7, 0x4f, v7
	s_mov_b32 s12, 0xfffffc0
	v_add_co_u32_e32 v32, vcc, s89, v20
	v_and_or_b32 v16, v17, s12, v16
	v_mul_u32_u24_e32 v7, 0x48, v7
	v_addc_co_u32_e32 v33, vcc, 0, v21, vcc
	v_mul_lo_u32 v14, v14, s54
	v_mad_u64_u32 v[100:101], s[12:13], v16, s54, v[6:7]
	s_barrier
	global_load_dwordx4 v[36:39], v[4:5], off
	global_load_dwordx4 v[40:43], v[8:9], off
	global_load_dwordx4 v[44:47], v[10:11], off
	global_load_dwordx4 v[48:51], v[12:13], off
	global_load_dwordx4 v[52:55], v[20:21], off
	global_load_dwordx4 v[56:59], v[22:23], off
	global_load_dwordx4 v[60:63], v[24:25], off
	global_load_dwordx4 v[64:67], v[32:33], off
	v_lshl_add_u32 v104, v15, 1, v14
	v_lshl_add_u32 v101, v7, 1, v6
	global_load_dwordx4 v[4:7], v[4:5], off offset:128
	s_nop 0
	global_load_dwordx4 v[16:19], v[8:9], off offset:128
	s_nop 0
	global_load_dwordx4 v[8:11], v[10:11], off offset:128
	s_nop 0
	global_load_dwordx4 v[12:15], v[12:13], off offset:128
	s_nop 0
	global_load_dwordx4 v[28:31], v[20:21], off offset:128
	s_nop 0
	global_load_dwordx4 v[20:23], v[22:23], off offset:128
	s_nop 0
	global_load_dwordx4 v[24:27], v[24:25], off offset:128
	s_nop 0
	global_load_dwordx4 v[32:35], v[32:33], off offset:128
	s_lshl_b32 s12, s19, 7
	s_sub_i32 s5, s12, s5
	s_lshl_b32 s12, s20, 13
	s_sub_i32 s12, s5, s12
	s_ashr_i32 s13, s12, 31
	s_lshl_b64 s[12:13], s[12:13], 11
	s_add_u32 s12, s15, s12
	v_add_u32_e32 v105, 0x9000, v104
	s_addc_u32 s13, s16, s13
	s_mov_b32 s5, -2
	s_waitcnt vmcnt(15)
	ds_write_b128 v104, v[36:39]
	s_waitcnt vmcnt(14)
	ds_write_b128 v104, v[40:43] offset:4608
	s_waitcnt vmcnt(13)
	ds_write_b128 v104, v[44:47] offset:9216
	s_waitcnt vmcnt(12)
	ds_write_b128 v104, v[48:51] offset:13824
	s_waitcnt vmcnt(11)
	ds_write_b128 v104, v[52:55] offset:18432
	s_waitcnt vmcnt(10)
	ds_write_b128 v104, v[56:59] offset:23040
	s_waitcnt vmcnt(9)
	ds_write_b128 v104, v[60:63] offset:27648
	s_waitcnt vmcnt(8)
	ds_write_b128 v104, v[64:67] offset:32256
	v_mov_b32_e32 v36, 0
	v_mov_b32_e32 v37, v36
	v_mov_b32_e32 v38, v36
	v_mov_b32_e32 v39, v36
	v_mov_b32_e32 v92, v36
	v_mov_b32_e32 v93, v36
	v_mov_b32_e32 v94, v36
	v_mov_b32_e32 v95, v36
	v_mov_b32_e32 v40, v36
	v_mov_b32_e32 v41, v36
	v_mov_b32_e32 v42, v36
	v_mov_b32_e32 v43, v36
	v_mov_b32_e32 v44, v36
	v_mov_b32_e32 v45, v36
	v_mov_b32_e32 v46, v36
	v_mov_b32_e32 v47, v36
	v_mov_b32_e32 v48, v36
	v_mov_b32_e32 v49, v36
	v_mov_b32_e32 v50, v36
	v_mov_b32_e32 v51, v36
	v_mov_b32_e32 v52, v36
	v_mov_b32_e32 v53, v36
	v_mov_b32_e32 v54, v36
	v_mov_b32_e32 v55, v36
	v_mov_b32_e32 v56, v36
	v_mov_b32_e32 v57, v36
	v_mov_b32_e32 v58, v36
	v_mov_b32_e32 v59, v36
	v_mov_b32_e32 v60, v36
	v_mov_b32_e32 v61, v36
	v_mov_b32_e32 v62, v36
	v_mov_b32_e32 v63, v36
	v_mov_b32_e32 v64, v36
	v_mov_b32_e32 v65, v36
	v_mov_b32_e32 v66, v36
	v_mov_b32_e32 v67, v36
	v_mov_b32_e32 v68, v36
	v_mov_b32_e32 v69, v36
	v_mov_b32_e32 v70, v36
	v_mov_b32_e32 v71, v36
	v_mov_b32_e32 v72, v36
	v_mov_b32_e32 v73, v36
	v_mov_b32_e32 v74, v36
	v_mov_b32_e32 v75, v36
	v_mov_b32_e32 v76, v36
	v_mov_b32_e32 v77, v36
	v_mov_b32_e32 v78, v36
	v_mov_b32_e32 v79, v36
	v_mov_b32_e32 v80, v36
	v_mov_b32_e32 v81, v36
	v_mov_b32_e32 v82, v36
	v_mov_b32_e32 v83, v36
	v_mov_b32_e32 v84, v36
	v_mov_b32_e32 v85, v36
	v_mov_b32_e32 v86, v36
	v_mov_b32_e32 v87, v36
	v_mov_b32_e32 v88, v36
	v_mov_b32_e32 v89, v36
	v_mov_b32_e32 v90, v36
	v_mov_b32_e32 v91, v36
	v_mov_b32_e32 v96, v36
	v_mov_b32_e32 v97, v36
	v_mov_b32_e32 v98, v36
	v_mov_b32_e32 v99, v36
	s_waitcnt lgkmcnt(0)
	s_barrier
	ds_read_b128 v[108:111], v100
	ds_read_b128 v[112:115], v101 offset:18432
	ds_read_b128 v[116:119], v100 offset:64
	ds_read_b128 v[120:123], v101 offset:18496
	ds_read_b128 v[124:127], v101 offset:20736
	ds_read_b128 v[132:135], v101 offset:23040
	ds_read_b128 v[140:143], v101 offset:25344
; DI void gemm_kloop(const bf16_t* __restrict__ A, int lda, const bf16_t* __restrict__ B, int ldb, int K, bf16_t* sm,
;                    f32x4 (&acc)[4][4]) {
;     ...
;   for (int kt = 0; kt < nk - 2; kt += 2) {
;     GLOAD(ra0, rb0, (kt + 2) << 6)
;     COMPUTE(0)
;     SSTORE(ra1, rb1, 1)
;     __syncthreads();
;     GLOAD(ra1, rb1, (kt + 3) << 6)
;     COMPUTE(1)
.LBB0_1739:
	ds_read_b128 v[128:131], v101 offset:20800
	ds_read_b128 v[136:139], v101 offset:23104
	ds_read_b128 v[144:147], v101 offset:25408
	s_waitcnt lgkmcnt(8)
	v_mfma_f32_16x16x32_bf16 v[96:99], v[108:111], v[112:115], v[96:99]
	v_lshl_add_u64 v[172:173], s[10:11], 0, v[102:103]
	v_add_co_u32_e32 v176, vcc, s85, v172
	s_waitcnt lgkmcnt(5)
	v_mfma_f32_16x16x32_bf16 v[88:91], v[108:111], v[124:127], v[88:91]
	v_addc_co_u32_e32 v177, vcc, 0, v173, vcc
	v_add_co_u32_e32 v178, vcc, s88, v172
	s_waitcnt lgkmcnt(3)
	v_mfma_f32_16x16x32_bf16 v[84:87], v[108:111], v[132:135], v[84:87]
	v_addc_co_u32_e32 v179, vcc, 0, v173, vcc
	v_add_co_u32_e32 v180, vcc, s89, v172
	s_waitcnt lgkmcnt(1)
	v_mfma_f32_16x16x32_bf16 v[80:83], v[108:111], v[140:143], v[80:83]
	ds_read_b128 v[108:111], v100 offset:2304
	ds_read_b128 v[148:151], v100 offset:2368
	v_lshl_add_u64 v[174:175], s[12:13], 0, v[102:103]
	v_addc_co_u32_e32 v181, vcc, 0, v173, vcc
	s_waitcnt lgkmcnt(1)
	v_mfma_f32_16x16x32_bf16 v[76:79], v[108:111], v[112:115], v[76:79]
	v_add_co_u32_e32 v208, vcc, s85, v174
	s_add_i32 s5, s5, 2
	v_mfma_f32_16x16x32_bf16 v[72:75], v[108:111], v[124:127], v[72:75]
	v_addc_co_u32_e32 v209, vcc, 0, v175, vcc
	v_add_co_u32_e32 v210, vcc, s88, v174
	v_mfma_f32_16x16x32_bf16 v[68:71], v[108:111], v[132:135], v[68:71]
	s_nop 0
	v_addc_co_u32_e32 v211, vcc, 0, v175, vcc
	v_add_co_u32_e32 v212, vcc, s89, v174
	v_mfma_f32_16x16x32_bf16 v[64:67], v[108:111], v[140:143], v[64:67]
	ds_read_b128 v[108:111], v100 offset:4608
	ds_read_b128 v[152:155], v100 offset:4672
	v_addc_co_u32_e32 v213, vcc, 0, v175, vcc
	s_waitcnt lgkmcnt(1)
	v_mfma_f32_16x16x32_bf16 v[60:63], v[108:111], v[112:115], v[60:63]
	s_add_u32 s12, s12, 0x100
	s_addc_u32 s13, s13, 0
	s_add_u32 s10, s10, 0x100
	v_mfma_f32_16x16x32_bf16 v[56:59], v[108:111], v[124:127], v[56:59]
	s_addc_u32 s11, s11, 0
	s_cmp_lt_u32 s5, 12
	v_mfma_f32_16x16x32_bf16 v[52:55], v[108:111], v[132:135], v[52:55]
	v_mfma_f32_16x16x32_bf16 v[48:51], v[108:111], v[140:143], v[48:51]
	ds_read_b128 v[108:111], v100 offset:6912
	ds_read_b128 v[156:159], v100 offset:6976
	s_waitcnt vmcnt(7)
	ds_write_b128 v104, v[4:7] offset:36864
	s_waitcnt vmcnt(6)
	ds_write_b128 v104, v[16:19] offset:41472
	s_waitcnt vmcnt(5)
	ds_write_b128 v104, v[8:11] offset:46080
	s_waitcnt vmcnt(4)
	ds_write_b128 v104, v[12:15] offset:50688
	s_waitcnt vmcnt(3)
	ds_write_b128 v104, v[28:31] offset:55296
	s_waitcnt lgkmcnt(6)
	v_mfma_f32_16x16x32_bf16 v[44:47], v[108:111], v[112:115], v[44:47]
	s_waitcnt vmcnt(2)
	ds_write_b128 v104, v[20:23] offset:59904
	s_waitcnt vmcnt(1)
	ds_write_b128 v104, v[24:27] offset:64512
	s_waitcnt vmcnt(0)
	ds_write_b128 v105, v[32:35] offset:32256
	global_load_dwordx4 v[112:115], v[174:175], off offset:256
	v_mfma_f32_16x16x32_bf16 v[40:43], v[108:111], v[124:127], v[40:43]
	v_mfma_f32_16x16x32_bf16 v[92:95], v[108:111], v[132:135], v[92:95]
	v_mfma_f32_16x16x32_bf16 v[36:39], v[108:111], v[140:143], v[36:39]
	global_load_dwordx4 v[108:111], v[172:173], off offset:256
	v_mfma_f32_16x16x32_bf16 v[96:99], v[116:119], v[120:123], v[96:99]
	v_mfma_f32_16x16x32_bf16 v[88:91], v[116:119], v[128:131], v[88:91]
	v_mfma_f32_16x16x32_bf16 v[4:7], v[116:119], v[136:139], v[84:87]
	v_mfma_f32_16x16x32_bf16 v[8:11], v[116:119], v[144:147], v[80:83]
	global_load_dwordx4 v[116:119], v[176:177], off offset:256
	global_load_dwordx4 v[124:127], v[178:179], off offset:256
	global_load_dwordx4 v[132:135], v[180:181], off offset:256
	v_mfma_f32_16x16x32_bf16 v[12:15], v[148:151], v[120:123], v[76:79]
	v_mfma_f32_16x16x32_bf16 v[16:19], v[148:151], v[128:131], v[72:75]
	v_mfma_f32_16x16x32_bf16 v[20:23], v[148:151], v[136:139], v[68:71]
	v_mfma_f32_16x16x32_bf16 v[24:27], v[148:151], v[144:147], v[64:67]
	v_mfma_f32_16x16x32_bf16 v[28:31], v[152:155], v[120:123], v[60:63]
	s_waitcnt lgkmcnt(8)
	v_mfma_f32_16x16x32_bf16 v[44:47], v[156:159], v[120:123], v[44:47]
	global_load_dwordx4 v[120:123], v[208:209], off offset:256
	global_load_dwordx4 v[140:143], v[210:211], off offset:256
	global_load_dwordx4 v[148:151], v[212:213], off offset:256
	s_waitcnt lgkmcnt(0)
	s_barrier
	ds_read_b128 v[60:63], v100 offset:36864
	v_mfma_f32_16x16x32_bf16 v[32:35], v[152:155], v[128:131], v[56:59]
	v_mfma_f32_16x16x32_bf16 v[40:43], v[156:159], v[128:131], v[40:43]
	v_mfma_f32_16x16x32_bf16 v[56:59], v[156:159], v[136:139], v[92:95]
	ds_read_b128 v[64:67], v101 offset:55296
	ds_read_b128 v[68:71], v100 offset:36928
	s_nop 0
	ds_read_b128 v[92:95], v101 offset:55360
	ds_read_b128 v[76:79], v101 offset:57600
	ds_read_b128 v[128:131], v101 offset:57664
	v_mfma_f32_16x16x32_bf16 v[52:55], v[152:155], v[136:139], v[52:55]
	ds_read_b128 v[84:87], v101 offset:59904
	ds_read_b128 v[136:139], v101 offset:59968
	v_mfma_f32_16x16x32_bf16 v[48:51], v[152:155], v[144:147], v[48:51]
	v_mfma_f32_16x16x32_bf16 v[36:39], v[156:159], v[144:147], v[36:39]
	s_waitcnt lgkmcnt(3)
	v_mfma_f32_16x16x32_bf16 v[80:83], v[60:63], v[76:79], v[88:91]
	s_nop 2
	ds_read_b128 v[88:91], v101 offset:62208
	ds_read_b128 v[144:147], v101 offset:62272
	v_mfma_f32_16x16x32_bf16 v[72:75], v[60:63], v[64:67], v[96:99]
	s_waitcnt lgkmcnt(3)
	v_mfma_f32_16x16x32_bf16 v[4:7], v[60:63], v[84:87], v[4:7]
	s_waitcnt lgkmcnt(1)
	v_mfma_f32_16x16x32_bf16 v[8:11], v[60:63], v[88:91], v[8:11]
	ds_read_b128 v[60:63], v100 offset:39168
	ds_read_b128 v[152:155], v100 offset:39232
	s_waitcnt lgkmcnt(1)
	v_mfma_f32_16x16x32_bf16 v[12:15], v[60:63], v[64:67], v[12:15]
	v_mfma_f32_16x16x32_bf16 v[16:19], v[60:63], v[76:79], v[16:19]
	v_mfma_f32_16x16x32_bf16 v[20:23], v[60:63], v[84:87], v[20:23]
	v_mfma_f32_16x16x32_bf16 v[24:27], v[60:63], v[88:91], v[24:27]
	ds_read_b128 v[60:63], v100 offset:41472
	ds_read_b128 v[156:159], v100 offset:41536
	s_waitcnt lgkmcnt(1)
; DI void gemm_kloop(const bf16_t* __restrict__ A, int lda, const bf16_t* __restrict__ B, int ldb, int K, bf16_t* sm,
;                    f32x4 (&acc)[4][4]) {
;     ...
;     COMPUTE(1)
;     SSTORE(ra0, rb0, 0)
;     __syncthreads();
;   }
;   COMPUTE(0)
;   SSTORE(ra1, rb1, 1)
;   __syncthreads();
;   COMPUTE(1)
;   __syncthreads();
	v_mfma_f32_16x16x32_bf16 v[28:31], v[60:63], v[64:67], v[28:31]
	v_mfma_f32_16x16x32_bf16 v[32:35], v[60:63], v[76:79], v[32:35]
	v_mfma_f32_16x16x32_bf16 v[52:55], v[60:63], v[84:87], v[52:55]
	v_mfma_f32_16x16x32_bf16 v[48:51], v[60:63], v[88:91], v[48:51]
	ds_read_b128 v[60:63], v100 offset:43776
	ds_read_b128 v[160:163], v100 offset:43840
	s_waitcnt lgkmcnt(1)
	v_mfma_f32_16x16x32_bf16 v[44:47], v[60:63], v[64:67], v[44:47]
	v_mfma_f32_16x16x32_bf16 v[40:43], v[60:63], v[76:79], v[40:43]
	v_mfma_f32_16x16x32_bf16 v[168:171], v[60:63], v[84:87], v[56:59]
	v_mfma_f32_16x16x32_bf16 v[36:39], v[60:63], v[88:91], v[36:39]
	v_mfma_f32_16x16x32_bf16 v[96:99], v[68:71], v[92:95], v[72:75]
	v_mfma_f32_16x16x32_bf16 v[88:91], v[68:71], v[128:131], v[80:83]
	v_mfma_f32_16x16x32_bf16 v[84:87], v[68:71], v[136:139], v[4:7]
	v_mfma_f32_16x16x32_bf16 v[80:83], v[68:71], v[144:147], v[8:11]
	s_nop 1
	global_load_dwordx4 v[4:7], v[172:173], off offset:384
	v_mfma_f32_16x16x32_bf16 v[76:79], v[152:155], v[92:95], v[12:15]
	v_mfma_f32_16x16x32_bf16 v[72:75], v[152:155], v[128:131], v[16:19]
	s_nop 2
	global_load_dwordx4 v[16:19], v[176:177], off offset:384
	global_load_dwordx4 v[8:11], v[178:179], off offset:384
	global_load_dwordx4 v[12:15], v[180:181], off offset:384
	v_mfma_f32_16x16x32_bf16 v[68:71], v[152:155], v[136:139], v[20:23]
	v_mfma_f32_16x16x32_bf16 v[64:67], v[152:155], v[144:147], v[24:27]
	v_mfma_f32_16x16x32_bf16 v[60:63], v[156:159], v[92:95], v[28:31]
	s_nop 2
	global_load_dwordx4 v[28:31], v[174:175], off offset:384
	global_load_dwordx4 v[20:23], v[208:209], off offset:384
	global_load_dwordx4 v[24:27], v[210:211], off offset:384
	v_mfma_f32_16x16x32_bf16 v[56:59], v[156:159], v[128:131], v[32:35]
	s_nop 2
	global_load_dwordx4 v[32:35], v[212:213], off offset:384
	v_mfma_f32_16x16x32_bf16 v[52:55], v[156:159], v[136:139], v[52:55]
	s_waitcnt vmcnt(14)
	ds_write_b128 v104, v[108:111]
	ds_write_b128 v104, v[112:115] offset:18432
	s_waitcnt vmcnt(13)
	ds_write_b128 v104, v[116:119] offset:4608
	s_waitcnt vmcnt(12)
	ds_write_b128 v104, v[124:127] offset:9216
	s_waitcnt vmcnt(11)
	ds_write_b128 v104, v[132:135] offset:13824
	s_waitcnt vmcnt(10)
	ds_write_b128 v104, v[120:123] offset:23040
	s_waitcnt vmcnt(9)
	ds_write_b128 v104, v[140:143] offset:27648
	s_waitcnt vmcnt(8)
	ds_write_b128 v104, v[148:151] offset:32256
	s_waitcnt lgkmcnt(0)
	s_barrier
	ds_read_b128 v[108:111], v100
	ds_read_b128 v[112:115], v101 offset:18432
	ds_read_b128 v[116:119], v100 offset:64
	ds_read_b128 v[120:123], v101 offset:18496
	ds_read_b128 v[124:127], v101 offset:20736
	ds_read_b128 v[132:135], v101 offset:23040
	ds_read_b128 v[140:143], v101 offset:25344
	v_mfma_f32_16x16x32_bf16 v[48:51], v[156:159], v[144:147], v[48:51]
	v_mfma_f32_16x16x32_bf16 v[44:47], v[160:163], v[92:95], v[44:47]
	v_mfma_f32_16x16x32_bf16 v[40:43], v[160:163], v[128:131], v[40:43]
	v_mfma_f32_16x16x32_bf16 v[92:95], v[160:163], v[136:139], v[168:171]
	v_mfma_f32_16x16x32_bf16 v[36:39], v[160:163], v[144:147], v[36:39]
	s_cbranch_scc1 .LBB0_1739
	ds_read_b128 v[108:111], v100
	ds_read_b128 v[112:115], v101 offset:18432
	ds_read_b128 v[116:119], v101 offset:20736
	ds_read_b128 v[120:123], v101 offset:23040
	ds_read_b128 v[124:127], v101 offset:25344
	v_readlane_b32 s10, v254, 53
	s_waitcnt lgkmcnt(3)
	v_mfma_f32_16x16x32_bf16 v[96:99], v[108:111], v[112:115], v[96:99]
	v_readlane_b32 s11, v254, 54
	s_and_b64 vcc, exec, s[10:11]
	s_waitcnt lgkmcnt(2)
	v_mfma_f32_16x16x32_bf16 v[88:91], v[108:111], v[116:119], v[88:91]
	s_waitcnt lgkmcnt(1)
	v_mfma_f32_16x16x32_bf16 v[84:87], v[108:111], v[120:123], v[84:87]
	s_waitcnt lgkmcnt(0)
	v_mfma_f32_16x16x32_bf16 v[80:83], v[108:111], v[124:127], v[80:83]
	ds_read_b128 v[108:111], v100 offset:2304
	s_waitcnt lgkmcnt(0)
	v_mfma_f32_16x16x32_bf16 v[76:79], v[108:111], v[112:115], v[76:79]
	v_mfma_f32_16x16x32_bf16 v[72:75], v[108:111], v[116:119], v[72:75]
	v_mfma_f32_16x16x32_bf16 v[68:71], v[108:111], v[120:123], v[68:71]
	v_mfma_f32_16x16x32_bf16 v[64:67], v[108:111], v[124:127], v[64:67]
	ds_read_b128 v[108:111], v100 offset:4608
	s_waitcnt lgkmcnt(0)
	v_mfma_f32_16x16x32_bf16 v[60:63], v[108:111], v[112:115], v[60:63]
	v_mfma_f32_16x16x32_bf16 v[56:59], v[108:111], v[116:119], v[56:59]
	v_mfma_f32_16x16x32_bf16 v[52:55], v[108:111], v[120:123], v[52:55]
	v_mfma_f32_16x16x32_bf16 v[48:51], v[108:111], v[124:127], v[48:51]
	ds_read_b128 v[108:111], v100 offset:6912
	s_waitcnt lgkmcnt(0)
	v_mfma_f32_16x16x32_bf16 v[44:47], v[108:111], v[112:115], v[44:47]
	ds_read_b128 v[112:115], v100 offset:64
	v_mfma_f32_16x16x32_bf16 v[40:43], v[108:111], v[116:119], v[40:43]
	ds_read_b128 v[116:119], v101 offset:20800
	v_mfma_f32_16x16x32_bf16 v[92:95], v[108:111], v[120:123], v[92:95]
	ds_read_b128 v[120:123], v101 offset:23104
	v_mfma_f32_16x16x32_bf16 v[36:39], v[108:111], v[124:127], v[36:39]
	ds_read_b128 v[108:111], v101 offset:18496
	ds_read_b128 v[124:127], v101 offset:25408
	s_waitcnt lgkmcnt(1)
	v_mfma_f32_16x16x32_bf16 v[96:99], v[112:115], v[108:111], v[96:99]
	v_mfma_f32_16x16x32_bf16 v[88:91], v[112:115], v[116:119], v[88:91]
	v_mfma_f32_16x16x32_bf16 v[84:87], v[112:115], v[120:123], v[84:87]
	s_waitcnt lgkmcnt(0)
	v_mfma_f32_16x16x32_bf16 v[80:83], v[112:115], v[124:127], v[80:83]
	ds_read_b128 v[112:115], v100 offset:2368
	s_waitcnt lgkmcnt(0)
	v_mfma_f32_16x16x32_bf16 v[76:79], v[112:115], v[108:111], v[76:79]
	v_mfma_f32_16x16x32_bf16 v[72:75], v[112:115], v[116:119], v[72:75]
	v_mfma_f32_16x16x32_bf16 v[68:71], v[112:115], v[120:123], v[68:71]
	v_mfma_f32_16x16x32_bf16 v[64:67], v[112:115], v[124:127], v[64:67]
	ds_read_b128 v[112:115], v100 offset:4672
	s_waitcnt lgkmcnt(0)
	v_mfma_f32_16x16x32_bf16 v[60:63], v[112:115], v[108:111], v[60:63]
	v_mfma_f32_16x16x32_bf16 v[56:59], v[112:115], v[116:119], v[56:59]
	v_mfma_f32_16x16x32_bf16 v[52:55], v[112:115], v[120:123], v[52:55]
	v_mfma_f32_16x16x32_bf16 v[48:51], v[112:115], v[124:127], v[48:51]
	ds_read_b128 v[112:115], v100 offset:6976
	s_waitcnt vmcnt(7)
	ds_write_b128 v104, v[4:7] offset:36864
	s_waitcnt vmcnt(6)
	ds_write_b128 v104, v[16:19] offset:41472
	s_waitcnt vmcnt(5)
	ds_write_b128 v104, v[8:11] offset:46080
	s_waitcnt vmcnt(4)
	ds_write_b128 v104, v[12:15] offset:50688
	s_waitcnt vmcnt(3)
	ds_write_b128 v104, v[28:31] offset:55296
	s_waitcnt vmcnt(2)
	ds_write_b128 v104, v[20:23] offset:59904
	s_waitcnt vmcnt(1)
	ds_write_b128 v104, v[24:27] offset:64512
	s_waitcnt vmcnt(0)
	ds_write_b128 v105, v[32:35] offset:32256
	s_waitcnt lgkmcnt(0)
	s_barrier
; DI void gemm_kloop(const bf16_t* __restrict__ A, int lda, const bf16_t* __restrict__ B, int ldb, int K, bf16_t* sm,
;                    f32x4 (&acc)[4][4]) {
;     ...
;   COMPUTE(1)
;   __syncthreads();
; DI void out_phase(const Params& p, int l, char* smem, const bool dry = false) {
;     ...
;     if (dry) {
;       if (acc[0][0][0] == 1.2345e30f) p.wi[0] = acc[1][1][1] + acc[2][2][2] + acc[3][3][3];
;       continue;
;     }
;     float xo[4][4][4];
; #pragma unroll
;     for (int i = 0; i < 4; i++)
; #pragma unroll
;       for (int r = 0; r < 4; r++) {
;         const int tok = mt * 128 + wm * 64 + i * 16 + g4 * 4 + r;
	ds_read_b128 v[4:7], v100 offset:36864
	ds_read_b128 v[12:15], v101 offset:55296
	v_mfma_f32_16x16x32_bf16 v[8:11], v[112:115], v[124:127], v[36:39]
	ds_read_b128 v[20:23], v101 offset:57600
	ds_read_b128 v[28:31], v101 offset:59904
	s_nop 0
	ds_read_b128 v[36:39], v101 offset:62208
	s_waitcnt lgkmcnt(3)
	v_mfma_f32_16x16x32_bf16 v[16:19], v[4:7], v[12:15], v[96:99]
	s_waitcnt lgkmcnt(2)
	v_mfma_f32_16x16x32_bf16 v[24:27], v[4:7], v[20:23], v[88:91]
	s_waitcnt lgkmcnt(1)
	v_mfma_f32_16x16x32_bf16 v[32:35], v[4:7], v[28:31], v[84:87]
	s_waitcnt lgkmcnt(0)
	v_mfma_f32_16x16x32_bf16 v[4:7], v[4:7], v[36:39], v[80:83]
	s_nop 2
	ds_read_b128 v[80:83], v100 offset:39168
	v_mfma_f32_16x16x32_bf16 v[40:43], v[112:115], v[116:119], v[40:43]
	ds_read_b128 v[116:119], v101 offset:57664
	s_waitcnt lgkmcnt(1)
	v_mfma_f32_16x16x32_bf16 v[76:79], v[80:83], v[12:15], v[76:79]
	v_mfma_f32_16x16x32_bf16 v[72:75], v[80:83], v[20:23], v[72:75]
	v_mfma_f32_16x16x32_bf16 v[68:71], v[80:83], v[28:31], v[68:71]
	v_mfma_f32_16x16x32_bf16 v[80:83], v[80:83], v[36:39], v[64:67]
	s_nop 2
	ds_read_b128 v[64:67], v100 offset:41472
	v_mfma_f32_16x16x32_bf16 v[92:95], v[112:115], v[120:123], v[92:95]
	ds_read_b128 v[120:123], v101 offset:59968
	s_waitcnt lgkmcnt(1)
	v_mfma_f32_16x16x32_bf16 v[102:105], v[64:67], v[36:39], v[48:51]
	s_nop 2
	ds_read_b128 v[48:51], v100 offset:43776
	v_mfma_f32_16x16x32_bf16 v[44:47], v[112:115], v[108:111], v[44:47]
	v_mfma_f32_16x16x32_bf16 v[84:87], v[64:67], v[12:15], v[60:63]
	s_waitcnt lgkmcnt(0)
	v_mfma_f32_16x16x32_bf16 v[108:111], v[48:51], v[12:15], v[44:47]
	ds_read_b128 v[12:15], v100 offset:36928
	v_mfma_f32_16x16x32_bf16 v[88:91], v[64:67], v[20:23], v[56:59]
	v_mfma_f32_16x16x32_bf16 v[112:115], v[48:51], v[20:23], v[40:43]
	ds_read_b128 v[20:23], v101 offset:55360
	s_waitcnt lgkmcnt(1)
	v_mfma_f32_16x16x32_bf16 v[60:63], v[12:15], v[120:123], v[32:35]
	s_nop 2
	ds_read_b128 v[32:35], v101 offset:62272
	v_mfma_f32_16x16x32_bf16 v[96:99], v[64:67], v[28:31], v[52:55]
	s_waitcnt lgkmcnt(0)
	v_mfma_f32_16x16x32_bf16 v[64:67], v[12:15], v[32:35], v[4:7]
	s_nop 2
	ds_read_b128 v[4:7], v100 offset:39232
	v_mfma_f32_16x16x32_bf16 v[28:31], v[48:51], v[28:31], v[92:95]
	v_mfma_f32_16x16x32_bf16 v[92:95], v[48:51], v[36:39], v[8:11]
	s_waitcnt lgkmcnt(0)
	v_mfma_f32_16x16x32_bf16 v[48:51], v[4:7], v[20:23], v[76:79]
	v_mfma_f32_16x16x32_bf16 v[44:47], v[4:7], v[116:119], v[72:75]
	v_mfma_f32_16x16x32_bf16 v[40:43], v[4:7], v[120:123], v[68:71]
	s_nop 1
	ds_read_b128 v[72:75], v100 offset:43840
	v_mfma_f32_16x16x32_bf16 v[36:39], v[4:7], v[32:35], v[80:83]
	ds_read_b128 v[4:7], v100 offset:41536
	v_lshl_add_u32 v68, s4, 7, v106
	s_mov_b64 s[4:5], -1
	v_mfma_f32_16x16x32_bf16 v[52:55], v[12:15], v[20:23], v[16:19]
	v_ashrrev_i32_e32 v69, 31, v68
	s_waitcnt lgkmcnt(0)
	s_barrier
	v_mfma_f32_16x16x32_bf16 v[56:59], v[12:15], v[116:119], v[24:27]
	v_mfma_f32_16x16x32_bf16 v[16:19], v[4:7], v[20:23], v[84:87]
	v_mfma_f32_16x16x32_bf16 v[12:15], v[4:7], v[116:119], v[88:91]
	v_mfma_f32_16x16x32_bf16 v[8:11], v[4:7], v[120:123], v[96:99]
	v_mfma_f32_16x16x32_bf16 v[4:7], v[4:7], v[32:35], v[102:105]
	v_mfma_f32_16x16x32_bf16 v[20:23], v[72:75], v[20:23], v[108:111]
	v_mfma_f32_16x16x32_bf16 v[24:27], v[72:75], v[116:119], v[112:115]
	v_mfma_f32_16x16x32_bf16 v[28:31], v[72:75], v[120:123], v[28:31]
	v_mfma_f32_16x16x32_bf16 v[32:35], v[72:75], v[32:35], v[92:95]
	s_cbranch_vccz .LBB0_1742
	s_mov_b64 s[4:5], 0
	v_mov_b64_e32 v[70:71], v[68:69]
